# attention loop x3 unroll with static ring slots (no per-step address VALU), persistent MFMA C-init block, trimmed common path, saddr LDS-DMA; O1S scratch addressing via saddr
# speedup vs baseline: 1.0471x; 1.0184x over previous
; __device__ __forceinline__ float swap_sum(float m) { auto rr = __builtin_amdgcn_permlane32_swap(__float_as_uint(m), __float_as_uint(m), false, false); return __uint_as_float(rr[0]) + __uint_as_float(rr[1]); }
; __device__ __forceinline__ void attn_unit(LAS unsigned char* lds, const bf16* __restrict__ Qb, const bf16* __restrict__ Kb, const bf16* __restrict__ VT, bf16* __restrict__ Y,
;                                           const float* __restrict__ gsub, float lam, int b, int h, int qb, float* o1scr) {
;     ...
;     {
;         const float li = lam * inv; float ss = 0.f;
; #pragma unroll
;         for (int e = 0; e < 4; ++e)
; #pragma unroll
;             for (int a = 0; a < 4; ++a) { const f32x4 v1 = *(const f32x4*)(o1scr + ((size_t)(e * 4 + a) * 512 + tid) * 4);
; #pragma unroll
;                 for (int k = 0; k < 4; ++k) { const float v = v1[k] - li * o[e][4 * a + k]; o[e][4 * a + k] = v; ss += v * v; } }
;         ss = swap_sum(ss);
;         const float rs = (1.0f - LAMBDA_INIT) / sqrtf(ss * (1.0f / 128.0f) + RMS_EPS);
.LBB0_557:
	v_lshlrev_b32_e32 v149, 4, v156
	v_add_u32_e32 v148, 0x1e000, v149
	global_load_dwordx4 v[184:187], v148, s[8:9]
	global_load_dwordx4 v[136:139], v149, s[8:9]
	global_load_dwordx4 v[64:67], v144, s[42:43]
	s_nop 0
	v_add_u32_e32 v148, 0x2000, v149
	global_load_dwordx4 v[176:179], v148, s[8:9]
	s_nop 0
	global_load_dwordx4 v[68:71], v144, s[42:43] offset:32
	v_add_u32_e32 v150, 0x4000, v149
	global_load_dwordx4 v[180:183], v150, s[8:9]
	global_load_dwordx4 v[72:75], v144, s[42:43] offset:64
	s_nop 0
	v_add_u32_e32 v148, 0x6000, v149
	global_load_dwordx4 v[172:175], v148, s[8:9]
	s_nop 0
	global_load_dwordx4 v[76:79], v144, s[42:43] offset:96
	v_add_u32_e32 v150, 0x1c000, v149
	global_load_dwordx4 v[100:103], v150, s[8:9]
	v_add_u32_e32 v148, 0x8000, v149
	global_load_dwordx4 v[188:191], v148, s[8:9]
	v_mul_f32_e32 v158, v157, v80
	v_add_u32_e32 v150, 0xa000, v149
	global_load_dwordx4 v[192:195], v150, s[8:9]
	v_add_u32_e32 v148, 0xc000, v149
	global_load_dwordx4 v[132:135], v148, s[8:9]
	v_add_u32_e32 v150, 0xe000, v149
	global_load_dwordx4 v[128:131], v150, s[8:9]
	v_add_u32_e32 v148, 0x10000, v149
	global_load_dwordx4 v[124:127], v148, s[8:9]
	v_add_u32_e32 v150, 0x12000, v149
	global_load_dwordx4 v[116:119], v150, s[8:9]
	global_load_dwordx4 v[80:83], v144, s[42:43] offset:128
	v_add_u32_e32 v148, 0x14000, v149
	global_load_dwordx4 v[120:123], v148, s[8:9]
	v_add_u32_e32 v150, 0x16000, v149
	global_load_dwordx4 v[112:115], v150, s[8:9]
	v_add_u32_e32 v148, 0x18000, v149
	global_load_dwordx4 v[108:111], v148, s[8:9]
	v_add_u32_e32 v150, 0x1a000, v149
	global_load_dwordx4 v[104:107], v150, s[8:9]
	v_lshlrev_b64 v[140:141], 11, v[146:147]
	v_lshlrev_b32_e32 v142, 3, v208
	v_mov_b32_e32 v143, v145
	v_mov_b32_e32 v148, v48
	v_mov_b32_e32 v149, v50
	v_mov_b32_e32 v50, v49
	v_mov_b32_e32 v48, v52
	v_mov_b32_e32 v49, v54
	v_mov_b32_e32 v54, v53
	v_mov_b32_e32 v52, v56
	v_mov_b32_e32 v53, v58
	v_mov_b32_e32 v58, v57
	v_lshl_add_u64 v[56:57], s[22:23], 0, v[140:141]
	v_mov_b32_e32 v164, v60
	v_lshl_add_u64 v[56:57], v[56:57], 0, v[142:143]
	v_mov_b32_e32 v165, v62
	v_mov_b32_e32 v62, v61
	global_load_dwordx4 v[84:87], v144, s[42:43] offset:160
	global_load_dwordx4 v[88:91], v144, s[42:43] offset:192
	global_load_dwordx4 v[92:95], v144, s[42:43] offset:224
	global_load_dwordx4 v[96:99], v144, s[42:43] offset:256
	s_add_i32 s88, s88, 1
	s_cmp_eq_u32 s88, 4
	s_waitcnt vmcnt(0)
	v_fma_f32 v142, -v12, v158, v184
	v_fma_f32 v60, -v13, v158, v185
	v_pk_fma_f32 v[140:141], v[14:15], v[158:159], v[186:187] op_sel_hi:[1,0,1] neg_lo:[1,0,0] neg_hi:[1,0,0]
	v_mov_b32_e32 v12, v136
	v_mov_b32_e32 v13, v138
	v_mov_b32_e32 v14, v176
	v_mov_b32_e32 v15, v178
	v_mov_b32_e32 v151, v66
	v_mov_b32_e32 v66, v65
	v_mov_b32_e32 v65, v182
	v_mov_b32_e32 v182, v181
	v_mov_b32_e32 v167, v174
	v_mov_b32_e32 v174, v173
	v_pk_fma_f32 v[162:163], v[148:149], v[158:159], v[12:13] op_sel_hi:[1,0,1] neg_lo:[1,0,0] neg_hi:[1,0,0]
	v_pk_fma_f32 v[154:155], v[48:49], v[158:159], v[14:15] op_sel_hi:[1,0,1] neg_lo:[1,0,0] neg_hi:[1,0,0]
	v_mov_b32_e32 v12, v32
	v_mov_b32_e32 v13, v34
	v_mov_b32_e32 v14, v188
	v_mov_b32_e32 v15, v190
	v_mov_b32_e32 v146, v68
	v_mov_b32_e32 v147, v70
	v_mov_b32_e32 v70, v69
	v_mov_b32_e32 v68, v72
	v_mov_b32_e32 v69, v74
	v_mov_b32_e32 v74, v73
	v_pk_fma_f32 v[72:73], v[58:59], v[158:159], v[182:183] op_sel_hi:[1,0,1] neg_lo:[1,0,0] neg_hi:[1,0,0]
	v_pk_fma_f32 v[58:59], v[62:63], v[158:159], v[174:175] op_sel_hi:[1,0,1] neg_lo:[1,0,0] neg_hi:[1,0,0]
	v_mov_b32_e32 v62, v76
	v_mov_b32_e32 v63, v78
	v_mov_b32_e32 v78, v77
	v_pk_fma_f32 v[76:77], v[12:13], v[158:159], v[14:15] op_sel_hi:[1,0,1] neg_lo:[1,0,0] neg_hi:[1,0,0]
	v_mov_b32_e32 v12, v36
	v_mov_b32_e32 v13, v38
	v_mov_b32_e32 v14, v192
	v_mov_b32_e32 v15, v194
	v_mov_b32_e32 v148, v80
	v_mov_b32_e32 v149, v82
	v_mov_b32_e32 v82, v81
	v_pk_fma_f32 v[80:81], v[12:13], v[158:159], v[14:15] op_sel_hi:[1,0,1] neg_lo:[1,0,0] neg_hi:[1,0,0]
	global_load_dwordx4 v[12:15], v144, s[42:43] offset:352
	v_mov_b32_e32 v138, v137
	v_pk_fma_f32 v[160:161], v[50:51], v[158:159], v[138:139] op_sel_hi:[1,0,1] neg_lo:[1,0,0] neg_hi:[1,0,0]
	global_load_dwordx4 v[48:51], v144, s[42:43] offset:288
	v_mov_b32_e32 v150, v64
	v_mov_b32_e32 v178, v177
	v_mov_b32_e32 v64, v180
	v_pk_fma_f32 v[152:153], v[54:55], v[158:159], v[178:179] op_sel_hi:[1,0,1] neg_lo:[1,0,0] neg_hi:[1,0,0]
	v_pk_fma_f32 v[136:137], v[52:53], v[158:159], v[64:65] op_sel_hi:[1,0,1] neg_lo:[1,0,0] neg_hi:[1,0,0]
	global_load_dwordx4 v[52:55], v144, s[42:43] offset:320
	v_mov_b32_e32 v38, v37
	v_mov_b32_e32 v194, v193
	v_mov_b32_e32 v34, v33
	v_mov_b32_e32 v190, v189
	v_pk_fma_f32 v[36:37], v[38:39], v[158:159], v[194:195] op_sel_hi:[1,0,1] neg_lo:[1,0,0] neg_hi:[1,0,0]
	v_mov_b32_e32 v32, v40
	v_mov_b32_e32 v33, v42
	v_mov_b32_e32 v42, v41
	v_mov_b32_e32 v38, v44
	v_mov_b32_e32 v39, v46
	v_mov_b32_e32 v40, v128
	v_mov_b32_e32 v41, v130
	v_pk_fma_f32 v[138:139], v[34:35], v[158:159], v[190:191] op_sel_hi:[1,0,1] neg_lo:[1,0,0] neg_hi:[1,0,0]
	v_mov_b32_e32 v34, v132
	v_mov_b32_e32 v35, v134
	v_mov_b32_e32 v134, v133
	v_pk_fma_f32 v[132:133], v[38:39], v[158:159], v[40:41] op_sel_hi:[1,0,1] neg_lo:[1,0,0] neg_hi:[1,0,0]
	v_mov_b32_e32 v39, v18
	v_mov_b32_e32 v41, v126
	v_mov_b32_e32 v18, v17
	v_mov_b32_e32 v126, v125
	v_mov_b32_e32 v166, v172
	v_mov_b32_e32 v46, v45
	v_mov_b32_e32 v130, v129
	v_mov_b32_e32 v38, v16
	v_mov_b32_e32 v40, v124
	v_pk_fma_f32 v[124:125], v[18:19], v[158:159], v[126:127] op_sel_hi:[1,0,1] neg_lo:[1,0,0] neg_hi:[1,0,0]
	v_mov_b32_e32 v16, v20
	v_mov_b32_e32 v17, v22
	v_mov_b32_e32 v18, v116
	v_mov_b32_e32 v19, v118
; __device__ __forceinline__ float swap_sum(float m) { auto rr = __builtin_amdgcn_permlane32_swap(__float_as_uint(m), __float_as_uint(m), false, false); return __uint_as_float(rr[0]) + __uint_as_float(rr[1]); }
; __device__ __forceinline__ void attn_unit(LAS unsigned char* lds, const bf16* __restrict__ Qb, const bf16* __restrict__ Kb, const bf16* __restrict__ VT, bf16* __restrict__ Y,
;                                           const float* __restrict__ gsub, float lam, int b, int h, int qb, float* o1scr) {
;     ...
;             for (int a = 0; a < 4; ++a) { const f32x4 v1 = *(const f32x4*)(o1scr + ((size_t)(e * 4 + a) * 512 + tid) * 4);
; #pragma unroll
;                 for (int k = 0; k < 4; ++k) { const float v = v1[k] - li * o[e][4 * a + k]; o[e][4 * a + k] = v; ss += v * v; } }
;         ss = swap_sum(ss);
;         const float rs = (1.0f - LAMBDA_INIT) / sqrtf(ss * (1.0f / 128.0f) + RMS_EPS);
	v_pk_fma_f32 v[64:65], v[164:165], v[158:159], v[166:167] op_sel_hi:[1,0,1] neg_lo:[1,0,0] neg_hi:[1,0,0]
	v_mov_b32_e32 v164, v84
	v_mov_b32_e32 v165, v86
	v_mov_b32_e32 v86, v85
	v_pk_fma_f32 v[84:85], v[32:33], v[158:159], v[34:35] op_sel_hi:[1,0,1] neg_lo:[1,0,0] neg_hi:[1,0,0]
	global_load_dwordx4 v[32:35], v144, s[42:43] offset:384
	v_pk_fma_f32 v[130:131], v[46:47], v[158:159], v[130:131] op_sel_hi:[1,0,1] neg_lo:[1,0,0] neg_hi:[1,0,0]
	v_pk_fma_f32 v[46:47], v[16:17], v[158:159], v[18:19] op_sel_hi:[1,0,1] neg_lo:[1,0,0] neg_hi:[1,0,0]
	v_mov_b32_e32 v22, v21
	v_mov_b32_e32 v16, v24
	v_mov_b32_e32 v17, v26
	v_mov_b32_e32 v26, v25
	v_mov_b32_e32 v20, v108
	v_mov_b32_e32 v21, v110
	v_mov_b32_e32 v110, v109
	v_mov_b32_e32 v18, v120
	v_mov_b32_e32 v19, v122
	v_pk_mul_f32 v[182:183], v[162:163], v[162:163]
	v_pk_mul_f32 v[184:185], v[160:161], v[160:161]
	v_pk_fma_f32 v[128:129], v[38:39], v[158:159], v[40:41] op_sel_hi:[1,0,1] neg_lo:[1,0,0] neg_hi:[1,0,0]
	v_pk_fma_f32 v[38:39], v[16:17], v[158:159], v[18:19] op_sel_hi:[1,0,1] neg_lo:[1,0,0] neg_hi:[1,0,0]
	v_mov_b32_e32 v16, v28
	v_mov_b32_e32 v17, v30
	v_mov_b32_e32 v18, v112
	v_mov_b32_e32 v19, v114
	v_mov_b32_e32 v30, v29
	v_mov_b32_e32 v114, v113
	v_pk_fma_f32 v[16:17], v[16:17], v[158:159], v[18:19] op_sel_hi:[1,0,1] neg_lo:[1,0,0] neg_hi:[1,0,0]
	v_pk_fma_f32 v[18:19], v[30:31], v[158:159], v[114:115] op_sel_hi:[1,0,1] neg_lo:[1,0,0] neg_hi:[1,0,0]
	v_add_f32_e32 v31, v182, v184
	v_add_f32_e32 v31, v183, v31
	v_pk_mul_f32 v[178:179], v[154:155], v[154:155]
	v_add_f32_e32 v31, v185, v31
	v_pk_mul_f32 v[180:181], v[152:153], v[152:153]
	v_add_f32_e32 v31, v178, v31
	v_add_f32_e32 v31, v180, v31
	v_add_f32_e32 v31, v179, v31
	v_pk_mul_f32 v[174:175], v[136:137], v[136:137]
	v_add_f32_e32 v31, v181, v31
	s_waitcnt vmcnt(3)
	v_mov_b32_e32 v24, v12
	v_mov_b32_e32 v25, v14
	v_mov_b32_e32 v14, v13
	v_mov_b32_e32 v12, v0
	v_mov_b32_e32 v13, v2
	v_mov_b32_e32 v2, v1
	v_pk_fma_f32 v[12:13], v[12:13], v[158:159], v[20:21] op_sel_hi:[1,0,1] neg_lo:[1,0,0] neg_hi:[1,0,0]
	v_pk_fma_f32 v[20:21], v[2:3], v[158:159], v[110:111] op_sel_hi:[1,0,1] neg_lo:[1,0,0] neg_hi:[1,0,0]
	global_load_dwordx4 v[0:3], v144, s[42:43] offset:416
	v_pk_mul_f32 v[176:177], v[72:73], v[72:73]
	v_add_f32_e32 v31, v174, v31
	v_add_f32_e32 v31, v176, v31
	v_add_f32_e32 v31, v175, v31
	v_pk_mul_f32 v[170:171], v[64:65], v[64:65]
	v_add_f32_e32 v31, v177, v31
	v_pk_mul_f32 v[172:173], v[58:59], v[58:59]
	v_add_f32_e32 v31, v170, v31
	v_add_f32_e32 v31, v172, v31
	v_add_f32_e32 v31, v171, v31
	v_pk_mul_f32 v[186:187], v[76:77], v[76:77]
	v_add_f32_e32 v31, v173, v31
	v_pk_mul_f32 v[188:189], v[138:139], v[138:139]
	v_add_f32_e32 v31, v186, v31
	v_add_f32_e32 v31, v188, v31
	v_add_f32_e32 v31, v187, v31
	v_pk_mul_f32 v[190:191], v[80:81], v[80:81]
	v_add_f32_e32 v31, v189, v31
	v_pk_mul_f32 v[192:193], v[36:37], v[36:37]
	v_add_f32_e32 v31, v190, v31
	v_add_f32_e32 v31, v192, v31
	v_add_f32_e32 v31, v191, v31
	v_pk_mul_f32 v[194:195], v[84:85], v[84:85]
	v_pk_fma_f32 v[42:43], v[42:43], v[158:159], v[134:135] op_sel_hi:[1,0,1] neg_lo:[1,0,0] neg_hi:[1,0,0]
	v_add_f32_e32 v31, v193, v31
	v_pk_mul_f32 v[196:197], v[42:43], v[42:43]
	v_add_f32_e32 v31, v194, v31
	v_add_f32_e32 v31, v196, v31
	v_add_f32_e32 v31, v195, v31
	v_pk_mul_f32 v[198:199], v[132:133], v[132:133]
	v_add_f32_e32 v31, v197, v31
	v_pk_mul_f32 v[200:201], v[130:131], v[130:131]
	v_add_f32_e32 v31, v198, v31
	v_add_f32_e32 v31, v200, v31
	v_add_f32_e32 v31, v199, v31
	v_pk_mul_f32 v[208:209], v[128:129], v[128:129]
	v_add_f32_e32 v31, v201, v31
	v_pk_mul_f32 v[210:211], v[124:125], v[124:125]
	v_add_f32_e32 v31, v208, v31
	v_add_f32_e32 v31, v210, v31
	v_mov_b32_e32 v118, v117
	v_add_f32_e32 v31, v209, v31
	v_mov_b32_e32 v166, v88
	v_mov_b32_e32 v167, v90
	v_mov_b32_e32 v90, v89
	v_mov_b32_e32 v126, v96
	v_mov_b32_e32 v127, v98
	v_mov_b32_e32 v98, v97
	v_pk_mul_f32 v[96:97], v[46:47], v[46:47]
	v_pk_fma_f32 v[88:89], v[22:23], v[158:159], v[118:119] op_sel_hi:[1,0,1] neg_lo:[1,0,0] neg_hi:[1,0,0]
	v_add_f32_e32 v31, v211, v31
	v_pk_mul_f32 v[116:117], v[88:89], v[88:89]
	v_add_f32_e32 v31, v96, v31
	v_add_f32_e32 v31, v116, v31
	v_mov_b32_e32 v122, v121
	v_add_f32_e32 v31, v97, v31
	v_mov_b32_e32 v134, v92
	v_mov_b32_e32 v135, v94
	v_mov_b32_e32 v94, v93
	s_waitcnt vmcnt(3)
	v_mov_b32_e32 v92, v48
	v_mov_b32_e32 v93, v50
	v_mov_b32_e32 v50, v49
	v_pk_mul_f32 v[48:49], v[38:39], v[38:39]
	v_pk_fma_f32 v[40:41], v[26:27], v[158:159], v[122:123] op_sel_hi:[1,0,1] neg_lo:[1,0,0] neg_hi:[1,0,0]
	v_add_f32_e32 v31, v117, v31
	v_pk_mul_f32 v[118:119], v[40:41], v[40:41]
	v_add_f32_e32 v31, v48, v31
	v_add_f32_e32 v31, v118, v31
	v_add_f32_e32 v31, v49, v31
	s_waitcnt vmcnt(2)
; __device__ __forceinline__ unsigned pk2(float lo, float hi) { return f2bf(lo) | (f2bf(hi) << 16); }
; __device__ __forceinline__ float swap_sum(float m) { auto rr = __builtin_amdgcn_permlane32_swap(__float_as_uint(m), __float_as_uint(m), false, false); return __uint_as_float(rr[0]) + __uint_as_float(rr[1]); }
; __device__ __forceinline__ void attn_unit(LAS unsigned char* lds, const bf16* __restrict__ Qb, const bf16* __restrict__ Kb, const bf16* __restrict__ VT, bf16* __restrict__ Y,
;                                           const float* __restrict__ gsub, float lam, int b, int h, int qb, float* o1scr) {
;     ...
;         ss = swap_sum(ss);
;         const float rs = (1.0f - LAMBDA_INIT) / sqrtf(ss * (1.0f / 128.0f) + RMS_EPS);
;         bf16* yp = Y + (tok0 + (size_t)qb * 256 + wid * 32 + r32) * 1024 + h * 128 + 4 * hi;
; #pragma unroll
;         for (int e = 0; e < 4; ++e)
; #pragma unroll
;             for (int a = 0; a < 4; ++a) { const f32x4 gg = *(const f32x4*)(gsub + 32 * e + 8 * a + 4 * hi);
;                 u32x2 w; w.x = pk2(o[e][4 * a] * rs * gg[0], o[e][4 * a + 1] * rs * gg[1]); w.y = pk2(o[e][4 * a + 2] * rs * gg[2], o[e][4 * a + 3] * rs * gg[3]);
;                 *(u32x2*)(yp + 32 * e + 8 * a) = w; }
	v_mov_b32_e32 v44, v52
	v_mov_b32_e32 v45, v54
	v_mov_b32_e32 v54, v53
	v_pk_mul_f32 v[52:53], v[16:17], v[16:17]
	v_add_f32_e32 v31, v119, v31
	v_pk_mul_f32 v[112:113], v[18:19], v[18:19]
	v_add_f32_e32 v31, v52, v31
	v_add_f32_e32 v31, v112, v31
	v_add_f32_e32 v31, v53, v31
	v_pk_mul_f32 v[114:115], v[12:13], v[12:13]
	v_add_f32_e32 v31, v113, v31
	v_pk_mul_f32 v[108:109], v[20:21], v[20:21]
	v_add_f32_e32 v31, v114, v31
	v_mov_b32_e32 v22, v4
	v_mov_b32_e32 v23, v6
	v_mov_b32_e32 v26, v104
	v_mov_b32_e32 v27, v106
	v_add_f32_e32 v31, v108, v31
	v_pk_fma_f32 v[22:23], v[22:23], v[158:159], v[26:27] op_sel_hi:[1,0,1] neg_lo:[1,0,0] neg_hi:[1,0,0]
	v_mov_b32_e32 v6, v5
	v_mov_b32_e32 v106, v105
	v_add_f32_e32 v31, v115, v31
	v_pk_mul_f32 v[110:111], v[22:23], v[22:23]
	v_pk_fma_f32 v[26:27], v[6:7], v[158:159], v[106:107] op_sel_hi:[1,0,1] neg_lo:[1,0,0] neg_hi:[1,0,0]
	v_add_f32_e32 v31, v109, v31
	v_pk_mul_f32 v[4:5], v[26:27], v[26:27]
	v_add_f32_e32 v31, v110, v31
	v_mov_b32_e32 v6, v8
	v_mov_b32_e32 v7, v10
	v_mov_b32_e32 v28, v100
	v_mov_b32_e32 v29, v102
	v_add_f32_e32 v4, v4, v31
	v_pk_fma_f32 v[28:29], v[6:7], v[158:159], v[28:29] op_sel_hi:[1,0,1] neg_lo:[1,0,0] neg_hi:[1,0,0]
	v_mov_b32_e32 v10, v9
	v_mov_b32_e32 v102, v101
	v_add_f32_e32 v4, v111, v4
	v_pk_mul_f32 v[6:7], v[28:29], v[28:29]
	v_pk_fma_f32 v[8:9], v[10:11], v[158:159], v[102:103] op_sel_hi:[1,0,1] neg_lo:[1,0,0] neg_hi:[1,0,0]
	v_add_f32_e32 v4, v5, v4
	v_pk_mul_f32 v[10:11], v[8:9], v[8:9]
	v_add_f32_e32 v4, v6, v4
	v_add_f32_e32 v4, v10, v4
	v_add_f32_e32 v4, v7, v4
	v_add_f32_e32 v4, v11, v4
	v_fmac_f32_e32 v4, v142, v142
	v_pk_mul_f32 v[168:169], v[140:141], v[140:141]
	v_fmac_f32_e32 v4, v60, v60
	v_add_f32_e32 v4, v168, v4
	v_add_f32_e32 v4, v169, v4
	v_mov_b32_e32 v5, v4
	s_nop 1
	v_permlane32_swap_b32_e32 v4, v5
	v_add_f32_e32 v4, v4, v5
	v_fmamk_f32 v4, v4, 0x3c000000, v205
	v_mul_f32_e32 v5, 0x4f800000, v4
	v_cmp_gt_f32_e32 vcc, s85, v4
	s_waitcnt vmcnt(0)
	v_mov_b32_e32 v10, v0
	v_mov_b32_e32 v30, v32
	v_cndmask_b32_e32 v4, v4, v5, vcc
	v_sqrt_f32_e32 v5, v4
	v_mov_b32_e32 v31, v34
	v_mov_b32_e32 v34, v33
	v_mov_b32_e32 v11, v2
	v_add_u32_e32 v0, -1, v5
	v_fma_f32 v6, -v0, v5, v4
	v_cmp_ge_f32_e64 s[0:1], 0, v6
	v_add_u32_e32 v6, 1, v5
	v_mov_b32_e32 v2, v1
	v_cndmask_b32_e64 v0, v5, v0, s[0:1]
	v_fma_f32 v5, -v6, v5, v4
	v_cmp_lt_f32_e64 s[0:1], 0, v5
	v_mov_b32_e32 v143, v140
	v_mov_b32_e32 v61, v141
	v_cndmask_b32_e64 v0, v0, v6, s[0:1]
	v_mul_f32_e32 v5, 0x37800000, v0
	v_cndmask_b32_e32 v0, v0, v5, vcc
	v_cmp_class_f32_e32 vcc, v4, v206
	s_nop 1
	v_cndmask_b32_e32 v0, v0, v4, vcc
	v_div_scale_f32 v32, s[0:1], v0, v0, s86
	v_rcp_f32_e32 v33, v32
	global_load_dwordx4 v[4:7], v144, s[42:43] offset:448
	v_fma_f32 v1, -v32, v33, 1.0
	v_fmac_f32_e32 v33, v1, v33
	v_div_scale_f32 v1, vcc, s86, v0, s86
	v_mul_f32_e32 v48, v1, v33
	v_fma_f32 v49, -v32, v48, v1
	v_fmac_f32_e32 v48, v49, v33
	v_fma_f32 v1, -v32, v48, v1
	v_div_fmas_f32 v1, v1, v33, v48
	v_div_fixup_f32 v0, v1, v0, s86
	v_pk_mul_f32 v[32:33], v[162:163], v[0:1] op_sel_hi:[1,0]
	v_pk_mul_f32 v[48:49], v[160:161], v[0:1] op_sel_hi:[1,0]
	v_pk_mul_f32 v[32:33], v[150:151], v[32:33]
	v_pk_mul_f32 v[48:49], v[66:67], v[48:49]
	v_and_b32_sdwa v1, v33, v207 dst_sel:DWORD dst_unused:UNUSED_PAD src0_sel:WORD_1 src1_sel:DWORD
	v_and_b32_sdwa v52, v32, v207 dst_sel:DWORD dst_unused:UNUSED_PAD src0_sel:WORD_1 src1_sel:DWORD
	v_add3_u32 v32, v32, v52, s87
	v_add3_u32 v1, v33, v1, s87
	v_and_b32_sdwa v33, v49, v207 dst_sel:DWORD dst_unused:UNUSED_PAD src0_sel:WORD_1 src1_sel:DWORD
	v_and_b32_sdwa v52, v48, v207 dst_sel:DWORD dst_unused:UNUSED_PAD src0_sel:WORD_1 src1_sel:DWORD
	v_add3_u32 v33, v49, v33, s87
	v_add3_u32 v48, v48, v52, s87
	v_and_b32_e32 v33, 0xffff0000, v33
	v_and_b32_e32 v48, 0xffff0000, v48
	v_or_b32_sdwa v33, v33, v1 dst_sel:DWORD dst_unused:UNUSED_PAD src0_sel:DWORD src1_sel:WORD_1
	v_or_b32_sdwa v32, v48, v32 dst_sel:DWORD dst_unused:UNUSED_PAD src0_sel:DWORD src1_sel:WORD_1
	global_store_dwordx2 v[56:57], v[32:33], off
	v_pk_mul_f32 v[32:33], v[154:155], v[0:1] op_sel_hi:[1,0]
	v_pk_mul_f32 v[48:49], v[152:153], v[0:1] op_sel_hi:[1,0]
	v_pk_mul_f32 v[32:33], v[146:147], v[32:33]
	v_pk_mul_f32 v[48:49], v[70:71], v[48:49]
	v_and_b32_sdwa v1, v33, v207 dst_sel:DWORD dst_unused:UNUSED_PAD src0_sel:WORD_1 src1_sel:DWORD
	v_and_b32_sdwa v52, v32, v207 dst_sel:DWORD dst_unused:UNUSED_PAD src0_sel:WORD_1 src1_sel:DWORD
	v_add3_u32 v32, v32, v52, s87
	v_add3_u32 v1, v33, v1, s87
	v_and_b32_sdwa v33, v49, v207 dst_sel:DWORD dst_unused:UNUSED_PAD src0_sel:WORD_1 src1_sel:DWORD
	v_and_b32_sdwa v52, v48, v207 dst_sel:DWORD dst_unused:UNUSED_PAD src0_sel:WORD_1 src1_sel:DWORD
	v_add3_u32 v33, v49, v33, s87
	v_add3_u32 v48, v48, v52, s87
	v_and_b32_e32 v33, 0xffff0000, v33
	v_and_b32_e32 v48, 0xffff0000, v48
	v_or_b32_sdwa v33, v33, v1 dst_sel:DWORD dst_unused:UNUSED_PAD src0_sel:DWORD src1_sel:WORD_1
	v_or_b32_sdwa v32, v48, v32 dst_sel:DWORD dst_unused:UNUSED_PAD src0_sel:DWORD src1_sel:WORD_1
	global_store_dwordx2 v[56:57], v[32:33], off offset:16
	v_pk_mul_f32 v[32:33], v[136:137], v[0:1] op_sel_hi:[1,0]
	v_pk_mul_f32 v[48:49], v[72:73], v[0:1] op_sel_hi:[1,0]
	v_pk_mul_f32 v[32:33], v[68:69], v[32:33]
	v_pk_mul_f32 v[48:49], v[74:75], v[48:49]
	v_and_b32_sdwa v1, v33, v207 dst_sel:DWORD dst_unused:UNUSED_PAD src0_sel:WORD_1 src1_sel:DWORD
	v_and_b32_sdwa v52, v32, v207 dst_sel:DWORD dst_unused:UNUSED_PAD src0_sel:WORD_1 src1_sel:DWORD
	v_add3_u32 v32, v32, v52, s87
	v_add3_u32 v1, v33, v1, s87
	v_and_b32_sdwa v33, v49, v207 dst_sel:DWORD dst_unused:UNUSED_PAD src0_sel:WORD_1 src1_sel:DWORD
; __device__ __forceinline__ unsigned pk2(float lo, float hi) { return f2bf(lo) | (f2bf(hi) << 16); }
; __device__ __forceinline__ void attn_unit(LAS unsigned char* lds, const bf16* __restrict__ Qb, const bf16* __restrict__ Kb, const bf16* __restrict__ VT, bf16* __restrict__ Y,
;                                           const float* __restrict__ gsub, float lam, int b, int h, int qb, float* o1scr) {
;     ...
;         for (int e = 0; e < 4; ++e)
; #pragma unroll
;             for (int a = 0; a < 4; ++a) { const f32x4 gg = *(const f32x4*)(gsub + 32 * e + 8 * a + 4 * hi);
;                 u32x2 w; w.x = pk2(o[e][4 * a] * rs * gg[0], o[e][4 * a + 1] * rs * gg[1]); w.y = pk2(o[e][4 * a + 2] * rs * gg[2], o[e][4 * a + 3] * rs * gg[3]);
;                 *(u32x2*)(yp + 32 * e + 8 * a) = w; }
	v_and_b32_sdwa v52, v48, v207 dst_sel:DWORD dst_unused:UNUSED_PAD src0_sel:WORD_1 src1_sel:DWORD
	v_add3_u32 v33, v49, v33, s87
	v_add3_u32 v48, v48, v52, s87
	v_and_b32_e32 v33, 0xffff0000, v33
	v_and_b32_e32 v48, 0xffff0000, v48
	v_or_b32_sdwa v33, v33, v1 dst_sel:DWORD dst_unused:UNUSED_PAD src0_sel:DWORD src1_sel:WORD_1
	v_or_b32_sdwa v32, v48, v32 dst_sel:DWORD dst_unused:UNUSED_PAD src0_sel:DWORD src1_sel:WORD_1
	global_store_dwordx2 v[56:57], v[32:33], off offset:32
	v_pk_mul_f32 v[32:33], v[64:65], v[0:1] op_sel_hi:[1,0]
	v_pk_mul_f32 v[48:49], v[58:59], v[0:1] op_sel_hi:[1,0]
	v_pk_mul_f32 v[32:33], v[62:63], v[32:33]
	v_pk_mul_f32 v[48:49], v[78:79], v[48:49]
	v_and_b32_sdwa v1, v33, v207 dst_sel:DWORD dst_unused:UNUSED_PAD src0_sel:WORD_1 src1_sel:DWORD
	v_and_b32_sdwa v52, v32, v207 dst_sel:DWORD dst_unused:UNUSED_PAD src0_sel:WORD_1 src1_sel:DWORD
	v_add3_u32 v32, v32, v52, s87
	v_add3_u32 v1, v33, v1, s87
	v_and_b32_sdwa v33, v49, v207 dst_sel:DWORD dst_unused:UNUSED_PAD src0_sel:WORD_1 src1_sel:DWORD
	v_and_b32_sdwa v52, v48, v207 dst_sel:DWORD dst_unused:UNUSED_PAD src0_sel:WORD_1 src1_sel:DWORD
	v_add3_u32 v33, v49, v33, s87
	v_add3_u32 v48, v48, v52, s87
	v_and_b32_e32 v33, 0xffff0000, v33
	v_and_b32_e32 v48, 0xffff0000, v48
	v_or_b32_sdwa v33, v33, v1 dst_sel:DWORD dst_unused:UNUSED_PAD src0_sel:DWORD src1_sel:WORD_1
	v_or_b32_sdwa v32, v48, v32 dst_sel:DWORD dst_unused:UNUSED_PAD src0_sel:DWORD src1_sel:WORD_1
	global_store_dwordx2 v[56:57], v[32:33], off offset:48
	v_pk_mul_f32 v[32:33], v[76:77], v[0:1] op_sel_hi:[1,0]
	v_pk_mul_f32 v[48:49], v[138:139], v[0:1] op_sel_hi:[1,0]
	v_pk_mul_f32 v[32:33], v[32:33], v[148:149]
	v_pk_mul_f32 v[48:49], v[48:49], v[82:83]
	v_and_b32_sdwa v1, v33, v207 dst_sel:DWORD dst_unused:UNUSED_PAD src0_sel:WORD_1 src1_sel:DWORD
	v_and_b32_sdwa v52, v32, v207 dst_sel:DWORD dst_unused:UNUSED_PAD src0_sel:WORD_1 src1_sel:DWORD
	v_add3_u32 v32, v32, v52, s87
	v_add3_u32 v1, v33, v1, s87
	v_and_b32_sdwa v33, v49, v207 dst_sel:DWORD dst_unused:UNUSED_PAD src0_sel:WORD_1 src1_sel:DWORD
	v_and_b32_sdwa v52, v48, v207 dst_sel:DWORD dst_unused:UNUSED_PAD src0_sel:WORD_1 src1_sel:DWORD
	v_add3_u32 v33, v49, v33, s87
	v_add3_u32 v48, v48, v52, s87
	v_and_b32_e32 v33, 0xffff0000, v33
	v_and_b32_e32 v48, 0xffff0000, v48
	v_or_b32_sdwa v33, v33, v1 dst_sel:DWORD dst_unused:UNUSED_PAD src0_sel:DWORD src1_sel:WORD_1
	v_or_b32_sdwa v32, v48, v32 dst_sel:DWORD dst_unused:UNUSED_PAD src0_sel:DWORD src1_sel:WORD_1
	global_store_dwordx2 v[56:57], v[32:33], off offset:64
	v_pk_mul_f32 v[32:33], v[80:81], v[0:1] op_sel_hi:[1,0]
	v_pk_mul_f32 v[36:37], v[36:37], v[0:1] op_sel_hi:[1,0]
	v_pk_mul_f32 v[32:33], v[32:33], v[164:165]
	v_pk_mul_f32 v[36:37], v[36:37], v[86:87]
	v_and_b32_sdwa v1, v33, v207 dst_sel:DWORD dst_unused:UNUSED_PAD src0_sel:WORD_1 src1_sel:DWORD
	v_and_b32_sdwa v48, v32, v207 dst_sel:DWORD dst_unused:UNUSED_PAD src0_sel:WORD_1 src1_sel:DWORD
	v_add3_u32 v32, v32, v48, s87
	v_add3_u32 v1, v33, v1, s87
	v_and_b32_sdwa v33, v37, v207 dst_sel:DWORD dst_unused:UNUSED_PAD src0_sel:WORD_1 src1_sel:DWORD
	v_and_b32_sdwa v48, v36, v207 dst_sel:DWORD dst_unused:UNUSED_PAD src0_sel:WORD_1 src1_sel:DWORD
	v_add3_u32 v33, v37, v33, s87
	v_add3_u32 v36, v36, v48, s87
	v_and_b32_e32 v33, 0xffff0000, v33
	v_and_b32_e32 v36, 0xffff0000, v36
	v_or_b32_sdwa v33, v33, v1 dst_sel:DWORD dst_unused:UNUSED_PAD src0_sel:DWORD src1_sel:WORD_1
	v_or_b32_sdwa v32, v36, v32 dst_sel:DWORD dst_unused:UNUSED_PAD src0_sel:DWORD src1_sel:WORD_1
	global_store_dwordx2 v[56:57], v[32:33], off offset:80
	v_pk_mul_f32 v[32:33], v[84:85], v[0:1] op_sel_hi:[1,0]
	v_pk_mul_f32 v[36:37], v[42:43], v[0:1] op_sel_hi:[1,0]
	v_pk_mul_f32 v[32:33], v[32:33], v[166:167]
	v_pk_mul_f32 v[36:37], v[36:37], v[90:91]
	v_and_b32_sdwa v1, v33, v207 dst_sel:DWORD dst_unused:UNUSED_PAD src0_sel:WORD_1 src1_sel:DWORD
	v_and_b32_sdwa v42, v32, v207 dst_sel:DWORD dst_unused:UNUSED_PAD src0_sel:WORD_1 src1_sel:DWORD
	v_add3_u32 v32, v32, v42, s87
	v_add3_u32 v1, v33, v1, s87
	v_and_b32_sdwa v33, v37, v207 dst_sel:DWORD dst_unused:UNUSED_PAD src0_sel:WORD_1 src1_sel:DWORD
	v_and_b32_sdwa v42, v36, v207 dst_sel:DWORD dst_unused:UNUSED_PAD src0_sel:WORD_1 src1_sel:DWORD
	v_add3_u32 v33, v37, v33, s87
	v_add3_u32 v36, v36, v42, s87
	v_and_b32_e32 v33, 0xffff0000, v33
	v_and_b32_e32 v36, 0xffff0000, v36
	v_or_b32_sdwa v33, v33, v1 dst_sel:DWORD dst_unused:UNUSED_PAD src0_sel:DWORD src1_sel:WORD_1
	v_or_b32_sdwa v32, v36, v32 dst_sel:DWORD dst_unused:UNUSED_PAD src0_sel:DWORD src1_sel:WORD_1
	global_store_dwordx2 v[56:57], v[32:33], off offset:96
	v_pk_mul_f32 v[32:33], v[132:133], v[0:1] op_sel_hi:[1,0]
	v_pk_mul_f32 v[36:37], v[130:131], v[0:1] op_sel_hi:[1,0]
	v_pk_mul_f32 v[32:33], v[32:33], v[134:135]
	v_pk_mul_f32 v[36:37], v[36:37], v[94:95]
	v_and_b32_sdwa v1, v33, v207 dst_sel:DWORD dst_unused:UNUSED_PAD src0_sel:WORD_1 src1_sel:DWORD
	v_and_b32_sdwa v42, v32, v207 dst_sel:DWORD dst_unused:UNUSED_PAD src0_sel:WORD_1 src1_sel:DWORD
	v_add3_u32 v32, v32, v42, s87
	v_add3_u32 v1, v33, v1, s87
	v_and_b32_sdwa v33, v37, v207 dst_sel:DWORD dst_unused:UNUSED_PAD src0_sel:WORD_1 src1_sel:DWORD
	v_and_b32_sdwa v42, v36, v207 dst_sel:DWORD dst_unused:UNUSED_PAD src0_sel:WORD_1 src1_sel:DWORD
	v_add3_u32 v33, v37, v33, s87
	v_add3_u32 v36, v36, v42, s87
	v_and_b32_e32 v33, 0xffff0000, v33
	v_and_b32_e32 v36, 0xffff0000, v36
	v_or_b32_sdwa v33, v33, v1 dst_sel:DWORD dst_unused:UNUSED_PAD src0_sel:DWORD src1_sel:WORD_1
	v_or_b32_sdwa v32, v36, v32 dst_sel:DWORD dst_unused:UNUSED_PAD src0_sel:DWORD src1_sel:WORD_1
	global_store_dwordx2 v[56:57], v[32:33], off offset:112
; __device__ __forceinline__ unsigned pk2(float lo, float hi) { return f2bf(lo) | (f2bf(hi) << 16); }
; __device__ __forceinline__ void attn_unit(LAS unsigned char* lds, const bf16* __restrict__ Qb, const bf16* __restrict__ Kb, const bf16* __restrict__ VT, bf16* __restrict__ Y,
;                                           const float* __restrict__ gsub, float lam, int b, int h, int qb, float* o1scr) {
;     ...
;         for (int e = 0; e < 4; ++e)
; #pragma unroll
;             for (int a = 0; a < 4; ++a) { const f32x4 gg = *(const f32x4*)(gsub + 32 * e + 8 * a + 4 * hi);
;                 u32x2 w; w.x = pk2(o[e][4 * a] * rs * gg[0], o[e][4 * a + 1] * rs * gg[1]); w.y = pk2(o[e][4 * a + 2] * rs * gg[2], o[e][4 * a + 3] * rs * gg[3]);
;                 *(u32x2*)(yp + 32 * e + 8 * a) = w; }
	v_pk_mul_f32 v[32:33], v[128:129], v[0:1] op_sel_hi:[1,0]
	v_pk_mul_f32 v[36:37], v[124:125], v[0:1] op_sel_hi:[1,0]
	v_pk_mul_f32 v[32:33], v[32:33], v[126:127]
	v_pk_mul_f32 v[36:37], v[36:37], v[98:99]
	v_and_b32_sdwa v1, v33, v207 dst_sel:DWORD dst_unused:UNUSED_PAD src0_sel:WORD_1 src1_sel:DWORD
	v_and_b32_sdwa v42, v32, v207 dst_sel:DWORD dst_unused:UNUSED_PAD src0_sel:WORD_1 src1_sel:DWORD
	v_add3_u32 v32, v32, v42, s87
	v_add3_u32 v1, v33, v1, s87
	v_and_b32_sdwa v33, v37, v207 dst_sel:DWORD dst_unused:UNUSED_PAD src0_sel:WORD_1 src1_sel:DWORD
	v_and_b32_sdwa v42, v36, v207 dst_sel:DWORD dst_unused:UNUSED_PAD src0_sel:WORD_1 src1_sel:DWORD
	v_add3_u32 v33, v37, v33, s87
	v_add3_u32 v36, v36, v42, s87
	v_and_b32_e32 v33, 0xffff0000, v33
	v_and_b32_e32 v36, 0xffff0000, v36
	v_or_b32_sdwa v33, v33, v1 dst_sel:DWORD dst_unused:UNUSED_PAD src0_sel:DWORD src1_sel:WORD_1
	v_or_b32_sdwa v32, v36, v32 dst_sel:DWORD dst_unused:UNUSED_PAD src0_sel:DWORD src1_sel:WORD_1
	global_store_dwordx2 v[56:57], v[32:33], off offset:128
	v_pk_mul_f32 v[32:33], v[46:47], v[0:1] op_sel_hi:[1,0]
	v_pk_mul_f32 v[36:37], v[88:89], v[0:1] op_sel_hi:[1,0]
	v_pk_mul_f32 v[32:33], v[32:33], v[92:93]
	v_pk_mul_f32 v[36:37], v[36:37], v[50:51]
	v_and_b32_sdwa v1, v33, v207 dst_sel:DWORD dst_unused:UNUSED_PAD src0_sel:WORD_1 src1_sel:DWORD
	v_and_b32_sdwa v42, v32, v207 dst_sel:DWORD dst_unused:UNUSED_PAD src0_sel:WORD_1 src1_sel:DWORD
	v_add3_u32 v32, v32, v42, s87
	v_add3_u32 v1, v33, v1, s87
	v_and_b32_sdwa v33, v37, v207 dst_sel:DWORD dst_unused:UNUSED_PAD src0_sel:WORD_1 src1_sel:DWORD
	v_and_b32_sdwa v42, v36, v207 dst_sel:DWORD dst_unused:UNUSED_PAD src0_sel:WORD_1 src1_sel:DWORD
	v_add3_u32 v33, v37, v33, s87
	v_add3_u32 v36, v36, v42, s87
	v_and_b32_e32 v33, 0xffff0000, v33
	v_and_b32_e32 v36, 0xffff0000, v36
	v_or_b32_sdwa v33, v33, v1 dst_sel:DWORD dst_unused:UNUSED_PAD src0_sel:DWORD src1_sel:WORD_1
	v_or_b32_sdwa v32, v36, v32 dst_sel:DWORD dst_unused:UNUSED_PAD src0_sel:DWORD src1_sel:WORD_1
	global_store_dwordx2 v[56:57], v[32:33], off offset:144
	v_pk_mul_f32 v[32:33], v[38:39], v[0:1] op_sel_hi:[1,0]
	v_pk_mul_f32 v[36:37], v[40:41], v[0:1] op_sel_hi:[1,0]
	v_pk_mul_f32 v[32:33], v[32:33], v[44:45]
	v_pk_mul_f32 v[40:41], v[36:37], v[54:55]
	v_and_b32_sdwa v36, v32, v207 dst_sel:DWORD dst_unused:UNUSED_PAD src0_sel:WORD_1 src1_sel:DWORD
	v_add3_u32 v32, v32, v36, s87
	global_load_dwordx4 v[36:39], v144, s[42:43] offset:480
	v_and_b32_sdwa v1, v33, v207 dst_sel:DWORD dst_unused:UNUSED_PAD src0_sel:WORD_1 src1_sel:DWORD
	v_add3_u32 v1, v33, v1, s87
	v_and_b32_sdwa v33, v41, v207 dst_sel:DWORD dst_unused:UNUSED_PAD src0_sel:WORD_1 src1_sel:DWORD
	v_add3_u32 v33, v41, v33, s87
	v_pk_mul_f32 v[16:17], v[16:17], v[0:1] op_sel_hi:[1,0]
	v_and_b32_e32 v33, 0xffff0000, v33
	v_pk_mul_f32 v[16:17], v[16:17], v[24:25]
	v_pk_mul_f32 v[18:19], v[18:19], v[0:1] op_sel_hi:[1,0]
	v_or_b32_sdwa v33, v33, v1 dst_sel:DWORD dst_unused:UNUSED_PAD src0_sel:DWORD src1_sel:WORD_1
	v_pk_mul_f32 v[14:15], v[18:19], v[14:15]
	v_and_b32_sdwa v1, v17, v207 dst_sel:DWORD dst_unused:UNUSED_PAD src0_sel:WORD_1 src1_sel:DWORD
	v_and_b32_sdwa v18, v16, v207 dst_sel:DWORD dst_unused:UNUSED_PAD src0_sel:WORD_1 src1_sel:DWORD
	v_add3_u32 v16, v16, v18, s87
	v_add3_u32 v1, v17, v1, s87
	v_and_b32_sdwa v17, v15, v207 dst_sel:DWORD dst_unused:UNUSED_PAD src0_sel:WORD_1 src1_sel:DWORD
	v_and_b32_sdwa v18, v14, v207 dst_sel:DWORD dst_unused:UNUSED_PAD src0_sel:WORD_1 src1_sel:DWORD
	v_add3_u32 v15, v15, v17, s87
	v_add3_u32 v14, v14, v18, s87
	v_and_b32_e32 v15, 0xffff0000, v15
	v_and_b32_e32 v14, 0xffff0000, v14
	v_or_b32_sdwa v15, v15, v1 dst_sel:DWORD dst_unused:UNUSED_PAD src0_sel:DWORD src1_sel:WORD_1
	v_or_b32_sdwa v14, v14, v16 dst_sel:DWORD dst_unused:UNUSED_PAD src0_sel:DWORD src1_sel:WORD_1
	v_pk_mul_f32 v[12:13], v[12:13], v[0:1] op_sel_hi:[1,0]
	global_store_dwordx2 v[56:57], v[14:15], off offset:176
	v_pk_mul_f32 v[12:13], v[12:13], v[30:31]
	v_pk_mul_f32 v[14:15], v[20:21], v[0:1] op_sel_hi:[1,0]
	v_and_b32_sdwa v1, v13, v207 dst_sel:DWORD dst_unused:UNUSED_PAD src0_sel:WORD_1 src1_sel:DWORD
	v_pk_mul_f32 v[14:15], v[14:15], v[34:35]
	v_and_b32_sdwa v16, v12, v207 dst_sel:DWORD dst_unused:UNUSED_PAD src0_sel:WORD_1 src1_sel:DWORD
	v_add3_u32 v12, v12, v16, s87
	v_add3_u32 v1, v13, v1, s87
	v_and_b32_sdwa v13, v15, v207 dst_sel:DWORD dst_unused:UNUSED_PAD src0_sel:WORD_1 src1_sel:DWORD
	v_and_b32_sdwa v16, v14, v207 dst_sel:DWORD dst_unused:UNUSED_PAD src0_sel:WORD_1 src1_sel:DWORD
	v_add3_u32 v13, v15, v13, s87
	v_add3_u32 v14, v14, v16, s87
	v_and_b32_e32 v13, 0xffff0000, v13
	v_and_b32_e32 v14, 0xffff0000, v14
	v_or_b32_sdwa v13, v13, v1 dst_sel:DWORD dst_unused:UNUSED_PAD src0_sel:DWORD src1_sel:WORD_1
	v_or_b32_sdwa v12, v14, v12 dst_sel:DWORD dst_unused:UNUSED_PAD src0_sel:DWORD src1_sel:WORD_1
	global_store_dwordx2 v[56:57], v[12:13], off offset:192
	v_pk_mul_f32 v[12:13], v[22:23], v[0:1] op_sel_hi:[1,0]
	v_and_b32_sdwa v42, v40, v207 dst_sel:DWORD dst_unused:UNUSED_PAD src0_sel:WORD_1 src1_sel:DWORD
	v_pk_mul_f32 v[10:11], v[12:13], v[10:11]
	v_pk_mul_f32 v[12:13], v[26:27], v[0:1] op_sel_hi:[1,0]
	v_and_b32_sdwa v1, v11, v207 dst_sel:DWORD dst_unused:UNUSED_PAD src0_sel:WORD_1 src1_sel:DWORD
	v_pk_mul_f32 v[2:3], v[12:13], v[2:3]
	v_and_b32_sdwa v12, v10, v207 dst_sel:DWORD dst_unused:UNUSED_PAD src0_sel:WORD_1 src1_sel:DWORD
	v_add3_u32 v10, v10, v12, s87
	v_add3_u32 v1, v11, v1, s87
	v_and_b32_sdwa v11, v3, v207 dst_sel:DWORD dst_unused:UNUSED_PAD src0_sel:WORD_1 src1_sel:DWORD
	v_and_b32_sdwa v12, v2, v207 dst_sel:DWORD dst_unused:UNUSED_PAD src0_sel:WORD_1 src1_sel:DWORD
	v_add3_u32 v3, v3, v11, s87
	v_add3_u32 v2, v2, v12, s87
	v_and_b32_e32 v3, 0xffff0000, v3
	v_and_b32_e32 v2, 0xffff0000, v2
	v_or_b32_sdwa v3, v3, v1 dst_sel:DWORD dst_unused:UNUSED_PAD src0_sel:DWORD src1_sel:WORD_1
	v_or_b32_sdwa v2, v2, v10 dst_sel:DWORD dst_unused:UNUSED_PAD src0_sel:DWORD src1_sel:WORD_1
	global_store_dwordx2 v[56:57], v[2:3], off offset:208
	v_pk_mul_f32 v[2:3], v[28:29], v[0:1] op_sel_hi:[1,0]
	s_waitcnt vmcnt(14)
; #define ATT_DMA(src, ldsoff) __builtin_amdgcn_global_load_lds((const unsigned*)(src), (LAS unsigned*)(lds + (ldsoff) + wofs), 16, 0, 0)
; __device__ __forceinline__ void attn_unit(LAS unsigned char* lds, const bf16* __restrict__ Qb, const bf16* __restrict__ Kb, const bf16* __restrict__ VT, bf16* __restrict__ Y,
;                                           const float* __restrict__ gsub, float lam, int b, int h, int qb, float* o1scr) {
;     int tid_ = threadIdx.x; asm volatile("" : "+v"(tid_));
;     const int tid = tid_, lane = tid & 63, wid = __builtin_amdgcn_readfirstlane(tid >> 6), r32 = lane & 31, hi = lane >> 5;
;     const size_t tok0 = (size_t)b * SEQ;
;     constexpr int KSL = 8192, VSL = 16384, VB0 = 3 * KSL;
;     const int kap = 16 * ((r32 >> 4) & 1) + 8 * ((r32 >> 2) & 1) + 4 * ((r32 >> 3) & 1) + (r32 & 3);
;     int kofs[4], vofs[4];
; #pragma unroll
;     for (int k = 0; k < 4; ++k) { kofs[k] = kap * 128 + (((2 * k + hi) ^ ((kap >> 1) & 7)) << 4); vofs[k] = r32 * 128 + (((2 * k + hi) ^ ((r32 >> 1) & 7)) << 4); }
;     const int lrow = tid >> 3, lc = (tid & 7) ^ ((lrow >> 1) & 7);
;     const int kcol = (lc < 4) ? 8 * lc : 128 + 8 * (lc - 4);
;     const unsigned wofs = (unsigned)wid * 1024u;
;     f32x16 o[4]; float inv = 0.f;
;     ...
; #pragma unroll 1
;     for (int mp = 0; mp < 2; ++mp) {
;         const int c1 = 256 * (h >> 1) + 32 * (2 * (h & 1) + mp);
;         const bf16* qp = Qb + (tok0 + (size_t)qb * 256 + wid * 32 + r32) * 512 + c1 + 8 * hi;
;         bf16x8 qr[4];
;         qr[0] = *(const bf16x8*)(qp); qr[1] = *(const bf16x8*)(qp + 16); qr[2] = *(const bf16x8*)(qp + 128); qr[3] = *(const bf16x8*)(qp + 144);
;         const bf16* kp = Kb + (tok0 + lrow) * 512 + c1 + kcol;
;         const bf16* vp = VT + ((size_t)((b * 4 + h) * 32) * 128 + lrow) * 64 + lc * 8;
;         ATT_DMA(kp, 0); ATT_DMA(vp, VB0); ATT_DMA(vp + 4096, VB0 + 8192); ATT_DMA(kp + (size_t)64 * 512, KSL);
; __global__ void __launch_bounds__(512, 2) fwd_mega(Args a) {
;     ...
;             for (int i = 0; i < 4; ++i) { const int bh = i * 32 + xc * 4 + (j >> 3), qb = j & 7;
;                 attn_unit(lds, QB, KB, VTB, YATT, a.in[11], lam, bh >> 2, bh & 3, qb, O1S); }
	v_mov_b32_e32 v10, v4
	v_mov_b32_e32 v11, v6
	v_pk_mul_f32 v[2:3], v[2:3], v[10:11]
	v_pk_mul_f32 v[8:9], v[8:9], v[0:1] op_sel_hi:[1,0]
	v_mov_b32_e32 v6, v5
	v_pk_mul_f32 v[4:5], v[8:9], v[6:7]
	v_and_b32_sdwa v1, v3, v207 dst_sel:DWORD dst_unused:UNUSED_PAD src0_sel:WORD_1 src1_sel:DWORD
	v_and_b32_sdwa v6, v2, v207 dst_sel:DWORD dst_unused:UNUSED_PAD src0_sel:WORD_1 src1_sel:DWORD
	v_add3_u32 v2, v2, v6, s87
	v_add3_u32 v1, v3, v1, s87
	v_and_b32_sdwa v3, v5, v207 dst_sel:DWORD dst_unused:UNUSED_PAD src0_sel:WORD_1 src1_sel:DWORD
	v_and_b32_sdwa v6, v4, v207 dst_sel:DWORD dst_unused:UNUSED_PAD src0_sel:WORD_1 src1_sel:DWORD
	v_add3_u32 v3, v5, v3, s87
	v_add3_u32 v4, v4, v6, s87
	v_and_b32_e32 v3, 0xffff0000, v3
	v_and_b32_e32 v4, 0xffff0000, v4
	v_or_b32_sdwa v3, v3, v1 dst_sel:DWORD dst_unused:UNUSED_PAD src0_sel:DWORD src1_sel:WORD_1
	v_or_b32_sdwa v2, v4, v2 dst_sel:DWORD dst_unused:UNUSED_PAD src0_sel:DWORD src1_sel:WORD_1
	global_store_dwordx2 v[56:57], v[2:3], off offset:224
	v_pk_mul_f32 v[2:3], v[142:143], v[0:1] op_sel_hi:[1,0]
	s_waitcnt vmcnt(4)
	v_mov_b32_e32 v4, v36
	v_mov_b32_e32 v5, v38
	v_pk_mul_f32 v[2:3], v[2:3], v[4:5]
	v_pk_mul_f32 v[0:1], v[60:61], v[0:1] op_sel_hi:[1,0]
	v_mov_b32_e32 v38, v37
	v_pk_mul_f32 v[0:1], v[0:1], v[38:39]
	v_and_b32_sdwa v4, v3, v207 dst_sel:DWORD dst_unused:UNUSED_PAD src0_sel:WORD_1 src1_sel:DWORD
	v_and_b32_sdwa v5, v2, v207 dst_sel:DWORD dst_unused:UNUSED_PAD src0_sel:WORD_1 src1_sel:DWORD
	v_add3_u32 v2, v2, v5, s87
	v_add3_u32 v3, v3, v4, s87
	v_and_b32_sdwa v4, v1, v207 dst_sel:DWORD dst_unused:UNUSED_PAD src0_sel:WORD_1 src1_sel:DWORD
	v_and_b32_sdwa v5, v0, v207 dst_sel:DWORD dst_unused:UNUSED_PAD src0_sel:WORD_1 src1_sel:DWORD
	v_add3_u32 v40, v40, v42, s87
	v_add3_u32 v1, v1, v4, s87
	v_add3_u32 v0, v0, v5, s87
	v_and_b32_e32 v40, 0xffff0000, v40
	v_and_b32_e32 v1, 0xffff0000, v1
	v_and_b32_e32 v0, 0xffff0000, v0
	v_or_b32_sdwa v32, v40, v32 dst_sel:DWORD dst_unused:UNUSED_PAD src0_sel:DWORD src1_sel:WORD_1
	v_or_b32_sdwa v1, v1, v3 dst_sel:DWORD dst_unused:UNUSED_PAD src0_sel:DWORD src1_sel:WORD_1
	v_or_b32_sdwa v0, v0, v2 dst_sel:DWORD dst_unused:UNUSED_PAD src0_sel:DWORD src1_sel:WORD_1
	global_store_dwordx2 v[56:57], v[32:33], off offset:160
	global_store_dwordx2 v[56:57], v[0:1], off offset:240
	s_cbranch_scc1 .LBB0_578
.LBB0_558:
	v_mov_b32_e32 v0, v156
	s_lshl_b32 s0, s88, 5
	v_lshlrev_b32_e32 v3, 1, v0
	v_lshrrev_b32_e32 v4, 1, v0
	v_and_b32_e32 v1, 31, v0
	v_lshrrev_b32_e32 v2, 5, v0
	v_and_b32_e32 v3, 8, v3
	v_and_b32_e32 v4, 4, v4
	v_and_b32_e32 v5, 19, v0
	v_bfe_u32 v6, v0, 1, 3
	v_bfe_u32 v208, v0, 5, 1
	v_or3_b32 v3, v3, v5, v4
	v_lshlrev_b32_e32 v5, 7, v1
	v_bitop3_b32 v2, v2, v6, 1 bitop3:0x6c
	v_lshlrev_b32_e32 v4, 7, v3
	v_lshrrev_b32_e32 v3, 1, v3
	v_lshl_or_b32 v210, v2, 4, v5
	v_or_b32_e32 v2, 2, v208
	v_bitop3_b32 v2, v3, v2, 7 bitop3:0x6c
	v_lshl_or_b32 v211, v2, 4, v4
	v_bitop3_b32 v2, v208, v6, 2 bitop3:0x36
	v_lshl_or_b32 v212, v2, 4, v5
	v_or_b32_e32 v2, 4, v208
	v_bitop3_b32 v2, v3, v2, 7 bitop3:0x6c
	v_lshl_or_b32 v213, v2, 4, v4
	v_bitop3_b32 v2, v208, v6, 4 bitop3:0x36
	v_lshl_or_b32 v214, v2, 4, v5
	v_or_b32_e32 v2, 6, v208
	s_add_i32 s0, s70, s0
	v_bitop3_b32 v7, v3, v208, 7 bitop3:0x6c
	v_bitop3_b32 v2, v3, v2, 7 bitop3:0x6c
	v_lshrrev_b32_e32 v3, 4, v0
	s_ashr_i32 s0, s0, 2
	v_readfirstlane_b32 s10, v0
	v_bitop3_b32 v10, v3, 7, v0 bitop3:0x48
	s_ashr_i32 s1, s0, 31
	s_ashr_i32 s33, s10, 6
	v_lshlrev_b32_e32 v3, 3, v10
	v_lshl_or_b32 v209, v7, 4, v4
	v_lshl_or_b32 v215, v2, 4, v4
	v_bitop3_b32 v2, v208, v6, 6 bitop3:0x36
	s_lshl_b64 s[10:11], s[0:1], 11
	v_add_u32_e32 v4, 0x60, v3
	v_cmp_gt_u32_e32 vcc, 4, v10
	s_lshl_b32 s46, s33, 5
	v_or_b32_e32 v1, s71, v1
	v_lshl_or_b32 v216, v2, 4, v5
	v_cndmask_b32_e32 v6, v4, v3, vcc
	s_ashr_i32 s47, s46, 31
	v_or_b32_e32 v4, s10, v1
	v_mov_b32_e32 v5, s11
	v_lshl_add_u64 v[146:147], v[4:5], 0, s[46:47]
	v_ashrrev_i32_e32 v2, 3, v0
	v_lshlrev_b64 v[4:5], 10, v[146:147]
	v_lshl_add_u64 v[4:5], s[12:13], 0, v[4:5]
	v_lshlrev_b32_e32 v144, 4, v208
	v_ashrrev_i32_e32 v3, 31, v2
	v_lshl_add_u64 v[176:177], v[4:5], 0, v[144:145]
	v_lshl_add_u64 v[4:5], s[10:11], 0, v[2:3]
	s_lshl_b32 s10, s0, 7
	s_or_b32 s10, s10, s72
	s_ashr_i32 s11, s10, 31
	s_lshl_b32 s44, s33, 10
	v_lshlrev_b64 v[4:5], 10, v[4:5]
	s_lshl_b64 s[10:11], s[10:11], 14
	v_lshl_add_u64 v[4:5], s[4:5], 0, v[4:5]
	v_lshlrev_b32_e32 v6, 1, v6
	v_mov_b32_e32 v7, v145
	s_add_u32 s46, s6, s10
	v_lshl_add_u64 v[180:181], v[4:5], 0, v[6:7]
	s_addc_u32 s47, s7, s11
	v_lshlrev_b64 v[4:5], 7, v[2:3]
	v_ashrrev_i32_e32 v1, 31, v0
	v_lshl_add_u64 v[8:9], s[46:47], 0, v[4:5]
	s_mov_b64 s[46:47], 0x8000
	s_mov_b64 s[46:47], 0xa000
	s_mov_b64 s[46:47], 0xc000
	s_mov_b64 s[46:47], 0xe000
	s_mov_b64 s[46:47], 0x12000
	s_mov_b64 s[46:47], 0x14000
	s_mov_b64 s[46:47], 0x16000
	s_lshl_b64 s[0:1], s[0:1], 21
	v_lshlrev_b64 v[0:1], 10, v[2:3]
	s_mov_b64 s[46:47], 0x18000
	v_lshl_add_u64 v[0:1], s[0:1], 0, v[0:1]
	s_mov_b64 s[46:47], 0x1a000
	v_or_b32_e32 v0, v0, v6
	v_lshlrev_b32_e32 v10, 4, v10
	v_mov_b32_e32 v11, v145
	s_mov_b64 s[46:47], 0x1c000
	v_lshl_add_u64 v[194:195], s[36:37], 0, v[0:1]
	v_lshl_add_u64 v[0:1], s[10:11], 0, v[4:5]
	v_lshl_add_u64 v[184:185], v[8:9], 0, v[10:11]
	s_add_i32 s33, s44, 0
	s_mov_b64 s[46:47], 0x1e000
	v_or_b32_e32 v0, v0, v10
	v_lshl_add_u64 v[186:187], v[184:185], 0, s[38:39]
	v_lshl_add_u64 v[188:189], v[184:185], 0, s[40:41]
	v_lshl_add_u64 v[190:191], v[184:185], 0, s[60:61]
	v_add_u32_e32 v217, 0, v209
	v_add_u32_e32 v218, 0, v211
	v_add_u32_e32 v219, 0, v213
	v_add_u32_e32 v220, 0, v215
	v_lshl_add_u64 v[196:197], s[30:31], 0, v[0:1]
	s_mov_b64 s[0:1], -1
	s_add_i32 s89, s33, 0x6000
	s_add_i32 s90, s33, 0x8000
	s_add_i32 s91, s33, 0x2000
	s_add_i32 s92, s33, 0x4000
	s_add_i32 s93, s33, 0xa000
	s_add_i32 s94, s33, 0xc000
	s_mov_b32 s44, s45
	s_branch .LBB0_560

; template <bool FIRST, bool HAS_PREV> ...
;     ...
;     { const float nm = FIRST ? 0.f : -st.mrun;
; #pragma unroll
;       for (int i = 0; i < 16; ++i) { c0[i] = nm; c1[i] = nm; } }
; #pragma unroll
;     for (int ks = 0; ks < 2; ++ks) { DSR128(kf[2 * ks], ka[ks], 0); DSR128(kf[2 * ks + 1], ka[ks], 4096); }
;     asm volatile("s_waitcnt lgkmcnt(0)" : "+v"(kf[0]), "+v"(kf[1]), "+v"(kf[2]), "+v"(kf[3]));
; #pragma unroll
;     for (int ks = 0; ks < 2; ++ks) {
;         c0 = __builtin_amdgcn_mfma_f32_32x32x16_bf16(kf[2 * ks], qr[ks], c0, 0, 0, 0);
;         c1 = __builtin_amdgcn_mfma_f32_32x32x16_bf16(kf[2 * ks + 1], qr[ks], c1, 0, 0, 0);
;     }
;     __builtin_amdgcn_sched_barrier(0);
;     { bf16x8 kg[4];
; #pragma unroll
;       for (int ks = 0; ks < 2; ++ks) { DSR128(kg[2 * ks], ka[2 + ks], 0); DSR128(kg[2 * ks + 1], ka[2 + ks], 4096); }
;       asm volatile("s_waitcnt lgkmcnt(0)" : "+v"(kg[0]), "+v"(kg[1]), "+v"(kg[2]), "+v"(kg[3]));
; #pragma unroll
;       for (int ks = 0; ks < 2; ++ks) {
;           c0 = __builtin_amdgcn_mfma_f32_32x32x16_bf16(kg[2 * ks], qr[2 + ks], c0, 0, 0, 0);
; __device__ __forceinline__ void attn_unit(LAS unsigned char* lds, const bf16* __restrict__ Qb, const bf16* __restrict__ Kb, const bf16* __restrict__ VT, bf16* __restrict__ Y,
;                                           const float* __restrict__ gsub, float lam, int b, int h, int qb, float* o1scr) {
;     ...
;         const int c1 = 256 * (h >> 1) + 32 * (2 * (h & 1) + mp);
;         const bf16* qp = Qb + (tok0 + (size_t)qb * 256 + wid * 32 + r32) * 512 + c1 + 8 * hi;
;         bf16x8 qr[4];
;         qr[0] = *(const bf16x8*)(qp); qr[1] = *(const bf16x8*)(qp + 16); qr[2] = *(const bf16x8*)(qp + 128); qr[3] = *(const bf16x8*)(qp + 144);
;         const bf16* kp = Kb + (tok0 + lrow) * 512 + c1 + kcol;
;         const bf16* vp = VT + ((size_t)((b * 4 + h) * 32) * 128 + lrow) * 64 + lc * 8;
;         ATT_DMA(kp, 0); ATT_DMA(vp, VB0); ATT_DMA(vp + 4096, VB0 + 8192); ATT_DMA(kp + (size_t)64 * 512, KSL);
;         ATT_WAITBAR(0);
; #pragma unroll
;         for (int e = 0; e < 4; ++e)
; #pragma unroll
;             for (int i = 0; i < 16; ++i) o[e][i] = 0.f;
;         AttnState st; st.mrun = 0.f; st.l = 0.f;
;         bf16x8 pbp[4];
;         f32x16 sA, sB;
;         int s0 = 0, s1 = 1, s2 = 2;
;     ...
;         ATT_STEP(0, true, false);
.LBB0_560:
	s_or_b32 s44, s73, s44
	s_lshl_b64 s[82:83], s[44:45], 1
	v_lshl_add_u64 v[0:1], v[176:177], 0, s[82:83]
	global_load_dwordx4 v[96:99], v[0:1], off
	s_mov_b32 m0, s33
	v_lshl_add_u64 v[2:3], v[180:181], 0, s[82:83]
	global_load_dwordx4 v[100:103], v[0:1], off offset:32
	global_load_dwordx4 v[104:107], v[0:1], off offset:256
	global_load_dwordx4 v[108:111], v[0:1], off offset:288
	v_lshl_add_u64 v[0:1], v[2:3], 0, s[62:63]
	global_load_lds_dwordx4 v[2:3], off
	s_mov_b32 m0, s89
	v_lshl_add_u64 v[2:3], v[2:3], 0, s[64:65]
	global_load_lds_dwordx4 v[184:185], off
	s_mov_b32 m0, s90
	s_mov_b32 s44, s45
	global_load_lds_dwordx4 v[186:187], off
	s_mov_b32 m0, s91
	s_mov_b32 s46, s45
	global_load_lds_dwordx4 v[0:1], off
	s_waitcnt vmcnt(0) lgkmcnt(0)
	s_barrier
	s_mov_b32 m0, s92
	s_mov_b32 s47, s45
	global_load_lds_dwordx4 v[2:3], off
	s_mov_b32 m0, s93
	s_mov_b32 s48, s45
	global_load_lds_dwordx4 v[188:189], off
	s_mov_b32 m0, s94
	s_mov_b32 s49, s45
	global_load_lds_dwordx4 v[190:191], off
	ds_read_b128 v[0:3], v217 offset:0
	ds_read_b128 v[4:7], v217 offset:0x1000
	ds_read_b128 v[8:11], v218 offset:0
	ds_read_b128 v[48:51], v218 offset:0x1000
	s_mov_b32 s50, s45
	s_waitcnt lgkmcnt(0)
	s_mov_b32 s51, s45
	s_mov_b32 s52, s45
	s_mov_b32 s53, s45
	s_mov_b32 s54, s45
	s_mov_b32 s55, s45
	s_mov_b32 s56, s45
	s_mov_b32 s57, s45
	s_mov_b32 s58, s45
	s_mov_b32 s59, s45
	s_mov_b32 s74, 1
	s_waitcnt vmcnt(0)
	v_mfma_f32_32x32x16_bf16 v[16:31], v[0:3], v[96:99], 0
	v_mfma_f32_32x32x16_bf16 v[32:47], v[4:7], v[96:99], 0
	v_mfma_f32_32x32x16_bf16 v[16:31], v[8:11], v[100:103], v[16:31]
	v_mov_b64_e32 v[0:1], s[44:45]
	v_mov_b64_e32 v[2:3], s[46:47]
	v_mov_b64_e32 v[4:5], s[48:49]
	v_mov_b64_e32 v[6:7], s[50:51]
	v_mov_b64_e32 v[8:9], s[52:53]
	v_mov_b64_e32 v[10:11], s[54:55]
	v_mov_b64_e32 v[12:13], s[56:57]
	v_mfma_f32_32x32x16_bf16 v[32:47], v[48:51], v[100:103], v[32:47]
	v_mov_b64_e32 v[14:15], s[58:59]
	ds_read_b128 v[48:51], v219 offset:0
	ds_read_b128 v[52:55], v219 offset:0x1000
	ds_read_b128 v[56:59], v220 offset:0
	ds_read_b128 v[60:63], v220 offset:0x1000
	s_nop 0
	s_waitcnt lgkmcnt(0)
	s_nop 0
	v_mfma_f32_32x32x16_bf16 v[16:31], v[48:51], v[104:107], v[16:31]
	v_mfma_f32_32x32x16_bf16 v[32:47], v[52:55], v[104:107], v[32:47]
	v_mfma_f32_32x32x16_bf16 v[16:31], v[56:59], v[108:111], v[16:31]
	v_mfma_f32_32x32x16_bf16 v[32:47], v[60:63], v[108:111], v[32:47]
	s_nop 11
	v_max_f32_e32 v48, v33, v33
	v_max_f32_e32 v49, v17, v17
	v_max_f32_e32 v48, v49, v48
	v_max_f32_e32 v49, v34, v34
	v_max_f32_e32 v50, v18, v18
	v_max_f32_e32 v49, v50, v49
	v_max_f32_e32 v50, v35, v35
	v_max_f32_e32 v51, v19, v19
	v_max3_f32 v48, v16, v32, v48
	v_max_f32_e32 v50, v51, v50
	v_max3_f32 v48, v48, v49, v50
	v_max_f32_e32 v49, v36, v36
	v_max_f32_e32 v50, v20, v20
	v_max_f32_e32 v49, v50, v49
	v_max_f32_e32 v50, v37, v37
	v_max_f32_e32 v51, v21, v21
	v_max_f32_e32 v50, v51, v50
	v_max3_f32 v48, v48, v49, v50
	v_max_f32_e32 v49, v38, v38
	v_max_f32_e32 v50, v22, v22
	v_max_f32_e32 v49, v50, v49
	v_max_f32_e32 v50, v39, v39
	v_max_f32_e32 v51, v23, v23
	v_max_f32_e32 v50, v51, v50
	v_max3_f32 v48, v48, v49, v50
	v_max_f32_e32 v49, v40, v40
	v_max_f32_e32 v50, v24, v24
	v_max_f32_e32 v49, v50, v49
	v_max_f32_e32 v50, v41, v41
	v_max_f32_e32 v51, v25, v25
	v_max_f32_e32 v50, v51, v50
	v_max3_f32 v48, v48, v49, v50
	v_max_f32_e32 v49, v42, v42
	v_max_f32_e32 v50, v26, v26
	v_max_f32_e32 v49, v50, v49
	v_max_f32_e32 v50, v43, v43
	v_max_f32_e32 v51, v27, v27
	v_max_f32_e32 v50, v51, v50
	v_max3_f32 v48, v48, v49, v50
	v_max_f32_e32 v49, v44, v44
	v_max_f32_e32 v50, v28, v28
	v_max_f32_e32 v49, v50, v49
	v_max_f32_e32 v50, v45, v45
	v_max_f32_e32 v51, v29, v29
	v_max_f32_e32 v50, v51, v50
	v_max3_f32 v48, v48, v49, v50
	v_max_f32_e32 v49, v46, v46
	v_max_f32_e32 v50, v30, v30
	v_max_f32_e32 v49, v50, v49
	v_max_f32_e32 v50, v47, v47
	v_max_f32_e32 v51, v31, v31
	v_max_f32_e32 v50, v51, v50
	v_max3_f32 v48, v48, v49, v50
	v_mov_b32_e32 v49, v48
	s_nop 1
	v_permlane32_swap_b32_e32 v48, v49
	v_max_f32_e32 v49, v49, v49
	v_max_f32_e32 v48, v48, v48
	v_max_f32_e32 v49, v48, v49
	v_sub_f32_e32 v16, v16, v49
	v_sub_f32_e32 v32, v32, v49
	v_exp_f32_e32 v16, v16
	v_sub_f32_e32 v17, v17, v49
	v_exp_f32_e32 v32, v32
	v_sub_f32_e32 v33, v33, v49
	v_exp_f32_e32 v17, v17
	v_sub_f32_e32 v18, v18, v49
	v_exp_f32_e32 v33, v33
	v_sub_f32_e32 v34, v34, v49
	v_add_f32_e32 v48, 0, v16
	v_exp_f32_e32 v18, v18
	v_sub_f32_e32 v19, v19, v49
	v_add_f32_e32 v48, v32, v48
	v_exp_f32_e32 v34, v34
	v_sub_f32_e32 v35, v35, v49
	v_add_f32_e32 v48, v17, v48
	v_exp_f32_e32 v19, v19
	v_sub_f32_e32 v20, v20, v49
	v_add_f32_e32 v48, v33, v48
	v_exp_f32_e32 v35, v35
	v_sub_f32_e32 v36, v36, v49
	v_add_f32_e32 v48, v18, v48
	v_exp_f32_e32 v20, v20
	v_sub_f32_e32 v21, v21, v49
	v_add_f32_e32 v48, v34, v48
	v_exp_f32_e32 v36, v36
	v_sub_f32_e32 v37, v37, v49
	v_add_f32_e32 v48, v19, v48
	v_exp_f32_e32 v21, v21
	v_sub_f32_e32 v22, v22, v49
	v_add_f32_e32 v48, v35, v48
	v_exp_f32_e32 v37, v37
	v_sub_f32_e32 v38, v38, v49
	v_add_f32_e32 v48, v20, v48
	v_exp_f32_e32 v22, v22
	v_sub_f32_e32 v23, v23, v49
	v_add_f32_e32 v48, v36, v48
	v_exp_f32_e32 v38, v38
	v_sub_f32_e32 v39, v39, v49
	v_add_f32_e32 v48, v21, v48
	v_exp_f32_e32 v23, v23
	v_sub_f32_e32 v24, v24, v49
	v_add_f32_e32 v48, v37, v48
	v_exp_f32_e32 v39, v39
	v_sub_f32_e32 v40, v40, v49
	v_add_f32_e32 v48, v22, v48
	v_exp_f32_e32 v24, v24
	v_sub_f32_e32 v25, v25, v49
	v_add_f32_e32 v48, v38, v48
	v_exp_f32_e32 v40, v40
	v_sub_f32_e32 v41, v41, v49
	v_add_f32_e32 v48, v23, v48
	v_exp_f32_e32 v25, v25
	v_sub_f32_e32 v26, v26, v49
	v_add_f32_e32 v48, v39, v48
	v_exp_f32_e32 v41, v41
	v_sub_f32_e32 v42, v42, v49
	v_add_f32_e32 v48, v24, v48
	v_exp_f32_e32 v26, v26
	v_sub_f32_e32 v27, v27, v49
	v_add_f32_e32 v48, v40, v48
	v_exp_f32_e32 v42, v42
	v_sub_f32_e32 v43, v43, v49
	v_add_f32_e32 v48, v25, v48
	v_exp_f32_e32 v27, v27
	v_sub_f32_e32 v28, v28, v49
	v_add_f32_e32 v48, v41, v48
	v_exp_f32_e32 v43, v43
	v_sub_f32_e32 v44, v44, v49
	v_add_f32_e32 v48, v26, v48
	v_exp_f32_e32 v28, v28
	v_sub_f32_e32 v29, v29, v49
	v_add_f32_e32 v48, v42, v48
	v_exp_f32_e32 v44, v44
	v_sub_f32_e32 v45, v45, v49
	v_add_f32_e32 v48, v27, v48
	v_exp_f32_e32 v29, v29
	v_sub_f32_e32 v30, v30, v49
	v_add_f32_e32 v48, v43, v48
	v_exp_f32_e32 v45, v45
	v_sub_f32_e32 v46, v46, v49
	v_add_f32_e32 v48, v28, v48
	v_exp_f32_e32 v30, v30
	v_sub_f32_e32 v31, v31, v49
	v_add_f32_e32 v48, v44, v48
	v_exp_f32_e32 v46, v46
	v_sub_f32_e32 v47, v47, v49
	v_add_f32_e32 v48, v29, v48
	v_exp_f32_e32 v31, v31
	v_add_f32_e32 v48, v45, v48
	v_exp_f32_e32 v47, v47
	v_add_f32_e32 v48, v30, v48
	v_add_f32_e32 v48, v46, v48
	v_add_f32_e32 v48, v31, v48
	v_add_f32_e32 v48, v47, v48
	s_waitcnt vmcnt(3) lgkmcnt(0)
	s_barrier
; #define DSR128(dst, addr, off) asm volatile("ds_read_b128 %0, %1 offset:%2" : "=&v"(dst) : "v"(addr), "i"(off))
; template <bool FIRST, bool HAS_PREV> ...
;     ...
;     { const float nm = FIRST ? 0.f : -st.mrun;
; #pragma unroll
;       for (int i = 0; i < 16; ++i) { c0[i] = nm; c1[i] = nm; } }
; #pragma unroll
;     for (int ks = 0; ks < 2; ++ks) { DSR128(kf[2 * ks], ka[ks], 0); DSR128(kf[2 * ks + 1], ka[ks], 4096); }
;     asm volatile("s_waitcnt lgkmcnt(0)" : "+v"(kf[0]), "+v"(kf[1]), "+v"(kf[2]), "+v"(kf[3]));
; #pragma unroll
;     for (int ks = 0; ks < 2; ++ks) {
;         c0 = __builtin_amdgcn_mfma_f32_32x32x16_bf16(kf[2 * ks], qr[ks], c0, 0, 0, 0);
;         c1 = __builtin_amdgcn_mfma_f32_32x32x16_bf16(kf[2 * ks + 1], qr[ks], c1, 0, 0, 0);
;     }
;     __builtin_amdgcn_sched_barrier(0);
;     { bf16x8 kg[4];
; #pragma unroll
;       for (int ks = 0; ks < 2; ++ks) { DSR128(kg[2 * ks], ka[2 + ks], 0); DSR128(kg[2 * ks + 1], ka[2 + ks], 4096); }
;       asm volatile("s_waitcnt lgkmcnt(0)" : "+v"(kg[0]), "+v"(kg[1]), "+v"(kg[2]), "+v"(kg[3]));
; #pragma unroll
;       for (int ks = 0; ks < 2; ++ks) {
;           c0 = __builtin_amdgcn_mfma_f32_32x32x16_bf16(kg[2 * ks], qr[2 + ks], c0, 0, 0, 0);
;           c1 = __builtin_amdgcn_mfma_f32_32x32x16_bf16(kg[2 * ks + 1], qr[2 + ks], c1, 0, 0, 0);
;       } }
;     __builtin_amdgcn_sched_barrier(0);
;     if (HAS_PREV) {
; #pragma unroll
;         for (int e = 0; e < 4; ++e) DSR128(vA[e], va[0], e * 4096);
;     }
;     float mx = fmaxf(c0[0], c1[0]);
; #pragma unroll
;     for (int i = 1; i < 16; ++i) mx = fmaxf(mx, fmaxf(c0[i], c1[i]));
;     mx = swap_max(mx);
;     float a = 1.0f;
;     { const float dl = FIRST ? mx : ((mx > 8.0f) ? mx : 0.f);
;       if (FIRST || __any(dl != 0.f)) {
; #pragma unroll
;           for (int i = 0; i < 16; ++i) { c0[i] -= dl; c1[i] -= dl; }
;           st.mrun += dl; if (!FIRST) a = __builtin_amdgcn_exp2f(-dl);
;       } }
; __device__ __forceinline__ void attn_unit(LAS unsigned char* lds, const bf16* __restrict__ Qb, const bf16* __restrict__ Kb, const bf16* __restrict__ VT, bf16* __restrict__ Y,
;                                           const float* __restrict__ gsub, float lam, int b, int h, int qb, float* o1scr) {
;     ...
;         AttnState st; st.mrun = 0.f; st.l = 0.f;
;         bf16x8 pbp[4];
;         f32x16 sA, sB;
;         int s0 = 0, s1 = 1, s2 = 2;
	v_pk_add_f32 v[198:199], v[48:49], 0 op_sel_hi:[1,0]
	v_xor_b32_e32 v158, 0x80000000, v49
	v_mov_b32_e32 v159, v158
	v_mov_b32_e32 v160, v158
	v_mov_b32_e32 v161, v158
	v_mov_b32_e32 v162, v158
	v_mov_b32_e32 v163, v158
	v_mov_b32_e32 v164, v158
	v_mov_b32_e32 v165, v158
	v_mov_b32_e32 v166, v158
	v_mov_b32_e32 v167, v158
	v_mov_b32_e32 v168, v158
	v_mov_b32_e32 v169, v158
	v_mov_b32_e32 v170, v158
	v_mov_b32_e32 v171, v158
	v_mov_b32_e32 v172, v158
	v_mov_b32_e32 v173, v158
	v_add_u32_e32 v174, 0x6000, v210
	v_add_u32_e32 v175, 0x6000, v212
	v_add_u32_e32 v178, 0x6000, v214
	v_add_u32_e32 v179, 0x6000, v216
	v_cvt_pk_bf16_f32 v124, v16, v17
	v_cvt_pk_bf16_f32 v125, v18, v19
	v_cvt_pk_bf16_f32 v126, v20, v21
	v_cvt_pk_bf16_f32 v127, v22, v23
	v_cvt_pk_bf16_f32 v120, v24, v25
	v_cvt_pk_bf16_f32 v121, v26, v27
	v_cvt_pk_bf16_f32 v122, v28, v29
	v_cvt_pk_bf16_f32 v123, v30, v31
	v_cvt_pk_bf16_f32 v116, v32, v33
	v_cvt_pk_bf16_f32 v117, v34, v35
	v_cvt_pk_bf16_f32 v118, v36, v37
	v_cvt_pk_bf16_f32 v119, v38, v39
	v_cvt_pk_bf16_f32 v112, v40, v41
	v_cvt_pk_bf16_f32 v113, v42, v43
	v_cvt_pk_bf16_f32 v114, v44, v45
	v_cvt_pk_bf16_f32 v115, v46, v47
	v_mov_b64_e32 v[30:31], v[14:15]
	v_mov_b64_e32 v[46:47], v[14:15]
	v_mov_b64_e32 v[62:63], v[14:15]
	v_lshl_add_u64 v[200:201], v[194:195], 0, s[82:83]
	v_subrev_u32_e32 v193, s36, v194
	s_add_u32 s54, s36, s82
	s_addc_u32 s55, s37, s83
	v_subrev_u32_e32 v182, s30, v196
	s_mov_b32 s56, s30
	s_mov_b32 s57, s31
	v_add_u32_e32 v182, 0x23008000, v182
	v_add_u32_e32 v183, 0x2000, v182
	s_mov_b32 s44, 0
	s_mov_b32 s52, 2
	s_mov_b64 s[46:47], 0
	v_mov_b64_e32 v[28:29], v[12:13]
	v_mov_b64_e32 v[26:27], v[10:11]
	v_mov_b64_e32 v[24:25], v[8:9]
	v_mov_b64_e32 v[22:23], v[6:7]
	v_mov_b64_e32 v[20:21], v[4:5]
	v_mov_b64_e32 v[18:19], v[2:3]
	v_mov_b64_e32 v[16:17], v[0:1]
	v_mov_b64_e32 v[44:45], v[12:13]
	v_mov_b64_e32 v[42:43], v[10:11]
	v_mov_b64_e32 v[40:41], v[8:9]
	v_mov_b64_e32 v[38:39], v[6:7]
	v_mov_b64_e32 v[36:37], v[4:5]
	v_mov_b64_e32 v[34:35], v[2:3]
	v_mov_b64_e32 v[32:33], v[0:1]
	s_mov_b32 s53, 1
	v_mov_b64_e32 v[60:61], v[12:13]
	v_mov_b64_e32 v[58:59], v[10:11]
	v_mov_b64_e32 v[56:57], v[8:9]
	v_mov_b64_e32 v[54:55], v[6:7]
	v_mov_b64_e32 v[52:53], v[4:5]
	v_mov_b64_e32 v[50:51], v[2:3]
	v_mov_b64_e32 v[48:49], v[0:1]
.LBB0_561:
	s_mov_b32 s51, 0
	ds_read_b128 v[128:131], v209 offset:8192
	ds_read_b128 v[132:135], v209 offset:12288
	ds_read_b128 v[136:139], v211 offset:8192
	ds_read_b128 v[140:143], v211 offset:12288
	ds_read_b128 v[222:225], v213 offset:8192
	ds_read_b128 v[226:229], v213 offset:12288
	ds_read_b128 v[230:233], v215 offset:8192
	ds_read_b128 v[234:237], v215 offset:12288
	s_waitcnt lgkmcnt(4)
	v_mfma_f32_32x32x16_bf16 v[80:95], v[128:131], v[96:99], v[158:173]
	v_mfma_f32_32x32x16_bf16 v[64:79], v[132:135], v[96:99], v[158:173]
	v_mfma_f32_32x32x16_bf16 v[80:95], v[136:139], v[100:103], v[80:95]
	v_mfma_f32_32x32x16_bf16 v[64:79], v[140:143], v[100:103], v[64:79]
	s_waitcnt lgkmcnt(0)
	v_mfma_f32_32x32x16_bf16 v[80:95], v[222:225], v[104:107], v[80:95]
	v_mfma_f32_32x32x16_bf16 v[64:79], v[226:229], v[104:107], v[64:79]
	v_mfma_f32_32x32x16_bf16 v[80:95], v[230:233], v[108:111], v[80:95]
	v_mfma_f32_32x32x16_bf16 v[64:79], v[234:237], v[108:111], v[64:79]
	ds_read_b128 v[140:143], v174 offset:0
	ds_read_b128 v[136:139], v174 offset:4096
	ds_read_b128 v[132:135], v174 offset:8192
	ds_read_b128 v[128:131], v174 offset:12288
	s_nop 6
	v_max3_f32 v202, v80, v81, v82
	v_max3_f32 v202, v202, v83, v84
	v_max3_f32 v202, v202, v85, v86
	v_max3_f32 v202, v202, v87, v88
	v_max3_f32 v202, v202, v89, v90
	v_max3_f32 v202, v202, v91, v92
	v_max3_f32 v202, v202, v93, v94
	v_max3_f32 v204, v64, v65, v66
	v_max3_f32 v204, v204, v67, v68
	v_max3_f32 v204, v204, v69, v70
	v_max3_f32 v204, v204, v71, v72
	v_max3_f32 v204, v204, v73, v74
	v_max3_f32 v204, v204, v75, v76
	v_max3_f32 v204, v204, v77, v78
	v_max3_f32 v202, v202, v95, v79
	v_max_f32_e32 v202, v202, v204
	v_mov_b32_e32 v204, v202
	s_nop 1
	v_permlane32_swap_b32_e32 v202, v204
	v_max_f32_e32 v202, v202, v204
	v_cmp_lt_f32_e32 vcc, s84, v202
	s_cbranch_vccnz .Lu3_rare_1
; #define DSR128(dst, addr, off) asm volatile("ds_read_b128 %0, %1 offset:%2" : "=&v"(dst) : "v"(addr), "i"(off))
; #define ATT_EXPS(E) do { _Pragma("unroll") for (int j = 0; j < 8; ++j) { const int i = (E) * 8 + j; \
;         if (i < 16) { c0[i] = __builtin_amdgcn_exp2f(c0[i]); ps += c0[i]; } else { c1[i - 16] = __builtin_amdgcn_exp2f(c1[i - 16]); ps += c1[i - 16]; } } \
;         asm volatile("" : "+v"(c0), "+v"(c1), "+v"(ps)); __builtin_amdgcn_sched_barrier(0); } while (0)
; #define ATT_PV(KK, VF) do { _Pragma("unroll") for (int e = 0; e < 4; ++e) o[e] = __builtin_amdgcn_mfma_f32_32x32x16_bf16(VF[e], pbp[KK], o[e], 0, 0, 0); } while (0)
; #define ATT_TIE(N, VF) asm volatile("s_waitcnt lgkmcnt(" #N ")" : "+v"(VF[0]), "+v"(VF[1]), "+v"(VF[2]), "+v"(VF[3]))
; template <bool FIRST, bool HAS_PREV> ...
;     ...
;     if (HAS_PREV) {
;         __builtin_amdgcn_sched_barrier(0);
; #pragma unroll
;         for (int e = 0; e < 4; ++e) DSR128(vB[e], va[1], e * 4096);
;         ATT_TIE(4, vA); ATT_PV(0, vA); ATT_EXPS(0);
; #pragma unroll
;         for (int e = 0; e < 4; ++e) DSR128(vA[e], va[2], e * 4096);
;         ATT_TIE(4, vB); ATT_PV(1, vB); ATT_EXPS(1);
; #pragma unroll
;         for (int e = 0; e < 4; ++e) DSR128(vB[e], va[3], e * 4096);
;         ATT_TIE(4, vA); ATT_PV(2, vA); ATT_EXPS(2);
;         ATT_TIE(0, vB); ATT_PV(3, vB); ATT_EXPS(3);
;     } else {
; #pragma unroll
;         for (int i = 0; i < 16; ++i) { c0[i] = __builtin_amdgcn_exp2f(c0[i]); ps += c0[i]; c1[i] = __builtin_amdgcn_exp2f(c1[i]); ps += c1[i]; }
;     }
;     ...
;     st.l = st.l * a + ps;
.Lu3_c_1:
	v_exp_f32_e32 v80, v80
	v_exp_f32_e32 v81, v81
	v_exp_f32_e32 v82, v82
	ds_read_b128 v[222:225], v175 offset:0
	ds_read_b128 v[226:229], v175 offset:4096
	ds_read_b128 v[230:233], v175 offset:8192
	ds_read_b128 v[234:237], v175 offset:12288
	s_waitcnt lgkmcnt(4)
	v_exp_f32_e32 v83, v83
	v_mfma_f32_32x32x16_bf16 v[48:63], v[140:143], v[124:127], v[48:63]
	v_exp_f32_e32 v84, v84
	v_exp_f32_e32 v85, v85
	v_exp_f32_e32 v86, v86
	v_exp_f32_e32 v87, v87
	v_mfma_f32_32x32x16_bf16 v[32:47], v[136:139], v[124:127], v[32:47]
	v_add_f32_e32 v192, v80, v81
	v_add_f32_e32 v192, v82, v192
	v_add_f32_e32 v192, v83, v192
	v_mfma_f32_32x32x16_bf16 v[16:31], v[132:135], v[124:127], v[16:31]
	v_add_f32_e32 v192, v84, v192
	v_add_f32_e32 v192, v85, v192
	v_add_f32_e32 v192, v86, v192
	v_add_f32_e32 v192, v87, v192
	v_mfma_f32_32x32x16_bf16 v[0:15], v[128:131], v[124:127], v[0:15]
	s_cmp_gt_u32 s53, 29
	s_cbranch_scc1 .Lu3_nok_1
	s_add_i32 m0, s33, 0x0
	s_nop 0
	global_load_lds_dwordx4 v193, s[54:55]
.Lu3_nok_1:
	v_exp_f32_e32 v88, v88
	v_exp_f32_e32 v89, v89
	v_exp_f32_e32 v90, v90
	v_exp_f32_e32 v91, v91
	ds_read_b128 v[124:127], v178 offset:0
	ds_read_b128 v[128:131], v178 offset:4096
	ds_read_b128 v[132:135], v178 offset:8192
	ds_read_b128 v[136:139], v178 offset:12288
	s_waitcnt lgkmcnt(4)
	v_add_f32_e32 v192, v192, v88
	v_mfma_f32_32x32x16_bf16 v[48:63], v[222:225], v[120:123], v[48:63]
	v_exp_f32_e32 v92, v92
	v_add_f32_e32 v192, v89, v192
	v_exp_f32_e32 v93, v93
	v_add_f32_e32 v192, v90, v192
	v_exp_f32_e32 v94, v94
	v_add_f32_e32 v192, v91, v192
	v_exp_f32_e32 v95, v95
	v_mfma_f32_32x32x16_bf16 v[32:47], v[226:229], v[120:123], v[32:47]
	v_add_f32_e32 v192, v92, v192
	v_add_f32_e32 v192, v93, v192
	v_add_f32_e32 v192, v94, v192
	v_add_f32_e32 v192, v95, v192
	v_mfma_f32_32x32x16_bf16 v[16:31], v[230:233], v[120:123], v[16:31]
	v_mfma_f32_32x32x16_bf16 v[0:15], v[234:237], v[120:123], v[0:15]
	s_cmp_eq_u32 s46, 0x78000
	s_cbranch_scc1 .Lu3_nov_1
	s_add_i32 m0, s33, 0xe000
	s_nop 0
	global_load_lds_dwordx4 v182, s[56:57]
	s_add_i32 m0, s33, 0x10000
	s_nop 0
	global_load_lds_dwordx4 v183, s[56:57]
.Lu3_nov_1:
	v_exp_f32_e32 v64, v64
	v_exp_f32_e32 v65, v65
	v_exp_f32_e32 v66, v66
	ds_read_b128 v[120:123], v179 offset:0
	ds_read_b128 v[140:143], v179 offset:4096
	ds_read_b128 v[222:225], v179 offset:8192
	ds_read_b128 v[226:229], v179 offset:12288
	s_waitcnt lgkmcnt(4)
	v_exp_f32_e32 v67, v67
	v_mfma_f32_32x32x16_bf16 v[48:63], v[124:127], v[116:119], v[48:63]
	v_add_f32_e32 v192, v192, v64
	v_exp_f32_e32 v68, v68
	v_add_f32_e32 v192, v65, v192
	v_exp_f32_e32 v69, v69
	v_add_f32_e32 v192, v66, v192
	v_exp_f32_e32 v70, v70
	v_add_f32_e32 v192, v67, v192
	v_mfma_f32_32x32x16_bf16 v[32:47], v[128:131], v[116:119], v[32:47]
	v_exp_f32_e32 v71, v71
	v_add_f32_e32 v192, v68, v192
	v_add_f32_e32 v192, v69, v192
	v_add_f32_e32 v192, v70, v192
	v_add_f32_e32 v192, v71, v192
	v_mfma_f32_32x32x16_bf16 v[16:31], v[132:135], v[116:119], v[16:31]
	v_mfma_f32_32x32x16_bf16 v[0:15], v[136:139], v[116:119], v[0:15]
	v_exp_f32_e32 v72, v72
	v_exp_f32_e32 v73, v73
	v_exp_f32_e32 v74, v74
	v_exp_f32_e32 v75, v75
	s_waitcnt lgkmcnt(0)
	v_add_f32_e32 v192, v192, v72
	v_mfma_f32_32x32x16_bf16 v[48:63], v[120:123], v[112:115], v[48:63]
	v_exp_f32_e32 v76, v76
	v_add_f32_e32 v192, v73, v192
	v_exp_f32_e32 v77, v77
	v_add_f32_e32 v192, v74, v192
	v_exp_f32_e32 v78, v78
	v_add_f32_e32 v192, v75, v192
	v_exp_f32_e32 v79, v79
	v_mfma_f32_32x32x16_bf16 v[32:47], v[140:143], v[112:115], v[32:47]
	v_add_f32_e32 v192, v76, v192
	v_add_f32_e32 v192, v77, v192
	v_add_f32_e32 v192, v78, v192
	v_add_f32_e32 v192, v79, v192
	v_mfma_f32_32x32x16_bf16 v[16:31], v[222:225], v[112:115], v[16:31]
	v_mfma_f32_32x32x16_bf16 v[0:15], v[226:229], v[112:115], v[0:15]
	s_cmp_lg_u32 s51, 0
	s_cbranch_scc1 .Lu3_resc_1
	v_add_f32_e32 v198, v198, v192
.Lu3_e_1:
	s_cmp_gt_u32 s53, 29
	s_cbranch_scc1 .Lu3_w0_1
	s_waitcnt vmcnt(3) lgkmcnt(0)
	s_branch .Lu3_wd_1

; template <bool FIRST, bool HAS_PREV> ...
;     ...
;     { const float nm = FIRST ? 0.f : -st.mrun;
; #pragma unroll
;       for (int i = 0; i < 16; ++i) { c0[i] = nm; c1[i] = nm; } }
; #pragma unroll
;     for (int ks = 0; ks < 2; ++ks) { DSR128(kf[2 * ks], ka[ks], 0); DSR128(kf[2 * ks + 1], ka[ks], 4096); }
;     asm volatile("s_waitcnt lgkmcnt(0)" : "+v"(kf[0]), "+v"(kf[1]), "+v"(kf[2]), "+v"(kf[3]));
; #pragma unroll
;     for (int ks = 0; ks < 2; ++ks) {
;         c0 = __builtin_amdgcn_mfma_f32_32x32x16_bf16(kf[2 * ks], qr[ks], c0, 0, 0, 0);
;         c1 = __builtin_amdgcn_mfma_f32_32x32x16_bf16(kf[2 * ks + 1], qr[ks], c1, 0, 0, 0);
;     }
;     __builtin_amdgcn_sched_barrier(0);
;     { bf16x8 kg[4];
; #pragma unroll
;       for (int ks = 0; ks < 2; ++ks) { DSR128(kg[2 * ks], ka[2 + ks], 0); DSR128(kg[2 * ks + 1], ka[2 + ks], 4096); }
;       asm volatile("s_waitcnt lgkmcnt(0)" : "+v"(kg[0]), "+v"(kg[1]), "+v"(kg[2]), "+v"(kg[3]));
; #pragma unroll
;       for (int ks = 0; ks < 2; ++ks) {
;           c0 = __builtin_amdgcn_mfma_f32_32x32x16_bf16(kg[2 * ks], qr[2 + ks], c0, 0, 0, 0);
;           c1 = __builtin_amdgcn_mfma_f32_32x32x16_bf16(kg[2 * ks + 1], qr[2 + ks], c1, 0, 0, 0);
;       } }
;     __builtin_amdgcn_sched_barrier(0);
;     if (HAS_PREV) {
; #pragma unroll
;         for (int e = 0; e < 4; ++e) DSR128(vA[e], va[0], e * 4096);
;     }
;     float mx = fmaxf(c0[0], c1[0]);
; #pragma unroll
;     for (int i = 1; i < 16; ++i) mx = fmaxf(mx, fmaxf(c0[i], c1[i]));
;     mx = swap_max(mx);
;     float a = 1.0f;
;     ...
;     { u32x4 w;
;       w.x = pg8::cvt_pk_bf16(c0[0], c0[1]); w.y = pg8::cvt_pk_bf16(c0[2], c0[3]); w.z = pg8::cvt_pk_bf16(c0[4], c0[5]); w.w = pg8::cvt_pk_bf16(c0[6], c0[7]); pbp[0] = __builtin_bit_cast(bf16x8, w);
;       w.x = pg8::cvt_pk_bf16(c0[8], c0[9]); w.y = pg8::cvt_pk_bf16(c0[10], c0[11]); w.z = pg8::cvt_pk_bf16(c0[12], c0[13]); w.w = pg8::cvt_pk_bf16(c0[14], c0[15]); pbp[1] = __builtin_bit_cast(bf16x8, w);
;       w.x = pg8::cvt_pk_bf16(c1[0], c1[1]); w.y = pg8::cvt_pk_bf16(c1[2], c1[3]); w.z = pg8::cvt_pk_bf16(c1[4], c1[5]); w.w = pg8::cvt_pk_bf16(c1[6], c1[7]); pbp[2] = __builtin_bit_cast(bf16x8, w);
;       w.x = pg8::cvt_pk_bf16(c1[8], c1[9]); w.y = pg8::cvt_pk_bf16(c1[10], c1[11]); w.z = pg8::cvt_pk_bf16(c1[12], c1[13]); w.w = pg8::cvt_pk_bf16(c1[14], c1[15]); pbp[3] = __builtin_bit_cast(bf16x8, w); }
.Lu3_wd_1:
	s_barrier
	s_add_u32 s46, s46, 0x4000
	s_addc_u32 s47, s47, 0
	s_add_i32 s53, s53, 1
	s_add_u32 s54, s54, 0x10000
	s_addc_u32 s55, s55, 0
	s_add_u32 s56, s56, 0x4000
	s_addc_u32 s57, s57, 0
	v_cvt_pk_bf16_f32 v124, v80, v81
	v_cvt_pk_bf16_f32 v125, v82, v83
	v_cvt_pk_bf16_f32 v126, v84, v85
	v_cvt_pk_bf16_f32 v127, v86, v87
	v_cvt_pk_bf16_f32 v120, v88, v89
	v_cvt_pk_bf16_f32 v121, v90, v91
	v_cvt_pk_bf16_f32 v122, v92, v93
	v_cvt_pk_bf16_f32 v123, v94, v95
	v_cvt_pk_bf16_f32 v116, v64, v65
	v_cvt_pk_bf16_f32 v117, v66, v67
	v_cvt_pk_bf16_f32 v118, v68, v69
	v_cvt_pk_bf16_f32 v119, v70, v71
	v_cvt_pk_bf16_f32 v112, v72, v73
	v_cvt_pk_bf16_f32 v113, v74, v75
	v_cvt_pk_bf16_f32 v114, v76, v77
	v_cvt_pk_bf16_f32 v115, v78, v79
	s_cmp_eq_u32 s46, 0x7c000
	s_cbranch_scc1 .Lu3_exit
	s_mov_b32 s51, 0
	ds_read_b128 v[128:131], v209 offset:16384
	ds_read_b128 v[132:135], v209 offset:20480
	ds_read_b128 v[136:139], v211 offset:16384
	ds_read_b128 v[140:143], v211 offset:20480
	ds_read_b128 v[222:225], v213 offset:16384
	ds_read_b128 v[226:229], v213 offset:20480
	ds_read_b128 v[230:233], v215 offset:16384
	ds_read_b128 v[234:237], v215 offset:20480
	s_waitcnt lgkmcnt(4)
	v_mfma_f32_32x32x16_bf16 v[80:95], v[128:131], v[96:99], v[158:173]
	v_mfma_f32_32x32x16_bf16 v[64:79], v[132:135], v[96:99], v[158:173]
	v_mfma_f32_32x32x16_bf16 v[80:95], v[136:139], v[100:103], v[80:95]
	v_mfma_f32_32x32x16_bf16 v[64:79], v[140:143], v[100:103], v[64:79]
	s_waitcnt lgkmcnt(0)
	v_mfma_f32_32x32x16_bf16 v[80:95], v[222:225], v[104:107], v[80:95]
	v_mfma_f32_32x32x16_bf16 v[64:79], v[226:229], v[104:107], v[64:79]
	v_mfma_f32_32x32x16_bf16 v[80:95], v[230:233], v[108:111], v[80:95]
	v_mfma_f32_32x32x16_bf16 v[64:79], v[234:237], v[108:111], v[64:79]
	ds_read_b128 v[140:143], v174 offset:16384
	ds_read_b128 v[136:139], v174 offset:20480
	ds_read_b128 v[132:135], v174 offset:24576
	ds_read_b128 v[128:131], v174 offset:28672
	s_nop 6
	v_max3_f32 v202, v80, v81, v82
	v_max3_f32 v202, v202, v83, v84
	v_max3_f32 v202, v202, v85, v86
	v_max3_f32 v202, v202, v87, v88
	v_max3_f32 v202, v202, v89, v90
	v_max3_f32 v202, v202, v91, v92
	v_max3_f32 v202, v202, v93, v94
	v_max3_f32 v204, v64, v65, v66
	v_max3_f32 v204, v204, v67, v68
	v_max3_f32 v204, v204, v69, v70
	v_max3_f32 v204, v204, v71, v72
	v_max3_f32 v204, v204, v73, v74
	v_max3_f32 v204, v204, v75, v76
	v_max3_f32 v204, v204, v77, v78
	v_max3_f32 v202, v202, v95, v79
	v_max_f32_e32 v202, v202, v204
	v_mov_b32_e32 v204, v202
	s_nop 1
	v_permlane32_swap_b32_e32 v202, v204
	v_max_f32_e32 v202, v202, v204
	v_cmp_lt_f32_e32 vcc, s84, v202
	s_cbranch_vccnz .Lu3_rare_2
.Lu3_c_2:
	v_exp_f32_e32 v80, v80
	v_exp_f32_e32 v81, v81
	v_exp_f32_e32 v82, v82
	ds_read_b128 v[222:225], v175 offset:16384
	ds_read_b128 v[226:229], v175 offset:20480
	ds_read_b128 v[230:233], v175 offset:24576
	ds_read_b128 v[234:237], v175 offset:28672
	s_waitcnt lgkmcnt(4)
	v_exp_f32_e32 v83, v83
	v_mfma_f32_32x32x16_bf16 v[48:63], v[140:143], v[124:127], v[48:63]
	v_exp_f32_e32 v84, v84
	v_exp_f32_e32 v85, v85
	v_exp_f32_e32 v86, v86
	v_exp_f32_e32 v87, v87
	v_mfma_f32_32x32x16_bf16 v[32:47], v[136:139], v[124:127], v[32:47]
	v_add_f32_e32 v192, v80, v81
	v_add_f32_e32 v192, v82, v192
	v_add_f32_e32 v192, v83, v192
	v_mfma_f32_32x32x16_bf16 v[16:31], v[132:135], v[124:127], v[16:31]
	v_add_f32_e32 v192, v84, v192
	v_add_f32_e32 v192, v85, v192
	v_add_f32_e32 v192, v86, v192
	v_add_f32_e32 v192, v87, v192
	v_mfma_f32_32x32x16_bf16 v[0:15], v[128:131], v[124:127], v[0:15]
	s_cmp_gt_u32 s53, 29
	s_cbranch_scc1 .Lu3_nok_2
	s_add_i32 m0, s33, 0x2000
	s_nop 0
	global_load_lds_dwordx4 v193, s[54:55]
.Lu3_nok_2:
	v_exp_f32_e32 v88, v88
	v_exp_f32_e32 v89, v89
	v_exp_f32_e32 v90, v90
	v_exp_f32_e32 v91, v91
	ds_read_b128 v[124:127], v178 offset:16384
	ds_read_b128 v[128:131], v178 offset:20480
	ds_read_b128 v[132:135], v178 offset:24576
	ds_read_b128 v[136:139], v178 offset:28672
	s_waitcnt lgkmcnt(4)
	v_add_f32_e32 v192, v192, v88
	v_mfma_f32_32x32x16_bf16 v[48:63], v[222:225], v[120:123], v[48:63]
	v_exp_f32_e32 v92, v92
	v_add_f32_e32 v192, v89, v192
	v_exp_f32_e32 v93, v93
	v_add_f32_e32 v192, v90, v192
	v_exp_f32_e32 v94, v94
	v_add_f32_e32 v192, v91, v192
	v_exp_f32_e32 v95, v95
	v_mfma_f32_32x32x16_bf16 v[32:47], v[226:229], v[120:123], v[32:47]
	v_add_f32_e32 v192, v92, v192
	v_add_f32_e32 v192, v93, v192
	v_add_f32_e32 v192, v94, v192
	v_add_f32_e32 v192, v95, v192
	v_mfma_f32_32x32x16_bf16 v[16:31], v[230:233], v[120:123], v[16:31]
	v_mfma_f32_32x32x16_bf16 v[0:15], v[234:237], v[120:123], v[0:15]
	s_cmp_eq_u32 s46, 0x78000
	s_cbranch_scc1 .Lu3_nov_2
	s_add_i32 m0, s33, 0x6000
	s_nop 0
	global_load_lds_dwordx4 v182, s[56:57]
	s_add_i32 m0, s33, 0x8000
	s_nop 0
	global_load_lds_dwordx4 v183, s[56:57]
.Lu3_nov_2:
	v_exp_f32_e32 v64, v64
	v_exp_f32_e32 v65, v65
	v_exp_f32_e32 v66, v66
	ds_read_b128 v[120:123], v179 offset:16384
	ds_read_b128 v[140:143], v179 offset:20480
	ds_read_b128 v[222:225], v179 offset:24576
	ds_read_b128 v[226:229], v179 offset:28672
	s_waitcnt lgkmcnt(4)
	v_exp_f32_e32 v67, v67
	v_mfma_f32_32x32x16_bf16 v[48:63], v[124:127], v[116:119], v[48:63]
	v_add_f32_e32 v192, v192, v64
	v_exp_f32_e32 v68, v68
	v_add_f32_e32 v192, v65, v192
	v_exp_f32_e32 v69, v69
	v_add_f32_e32 v192, v66, v192
	v_exp_f32_e32 v70, v70
	v_add_f32_e32 v192, v67, v192
	v_mfma_f32_32x32x16_bf16 v[32:47], v[128:131], v[116:119], v[32:47]
	v_exp_f32_e32 v71, v71
	v_add_f32_e32 v192, v68, v192
	v_add_f32_e32 v192, v69, v192
	v_add_f32_e32 v192, v70, v192
	v_add_f32_e32 v192, v71, v192
	v_mfma_f32_32x32x16_bf16 v[16:31], v[132:135], v[116:119], v[16:31]
	v_mfma_f32_32x32x16_bf16 v[0:15], v[136:139], v[116:119], v[0:15]
	v_exp_f32_e32 v72, v72
	v_exp_f32_e32 v73, v73
	v_exp_f32_e32 v74, v74
	v_exp_f32_e32 v75, v75
	s_waitcnt lgkmcnt(0)
	v_add_f32_e32 v192, v192, v72
	v_mfma_f32_32x32x16_bf16 v[48:63], v[120:123], v[112:115], v[48:63]
	v_exp_f32_e32 v76, v76
	v_add_f32_e32 v192, v73, v192
	v_exp_f32_e32 v77, v77
	v_add_f32_e32 v192, v74, v192
	v_exp_f32_e32 v78, v78
	v_add_f32_e32 v192, v75, v192
	v_exp_f32_e32 v79, v79
	v_mfma_f32_32x32x16_bf16 v[32:47], v[140:143], v[112:115], v[32:47]
	v_add_f32_e32 v192, v76, v192
	v_add_f32_e32 v192, v77, v192
	v_add_f32_e32 v192, v78, v192
	v_add_f32_e32 v192, v79, v192
	v_mfma_f32_32x32x16_bf16 v[16:31], v[222:225], v[112:115], v[16:31]
	v_mfma_f32_32x32x16_bf16 v[0:15], v[226:229], v[112:115], v[0:15]
	s_cmp_lg_u32 s51, 0
	s_cbranch_scc1 .Lu3_resc_2
	v_add_f32_e32 v198, v198, v192

; template <bool FIRST, bool HAS_PREV> ...
;     ...
;     { const float nm = FIRST ? 0.f : -st.mrun;
; #pragma unroll
;       for (int i = 0; i < 16; ++i) { c0[i] = nm; c1[i] = nm; } }
; #pragma unroll
;     for (int ks = 0; ks < 2; ++ks) { DSR128(kf[2 * ks], ka[ks], 0); DSR128(kf[2 * ks + 1], ka[ks], 4096); }
;     asm volatile("s_waitcnt lgkmcnt(0)" : "+v"(kf[0]), "+v"(kf[1]), "+v"(kf[2]), "+v"(kf[3]));
; #pragma unroll
;     for (int ks = 0; ks < 2; ++ks) {
;         c0 = __builtin_amdgcn_mfma_f32_32x32x16_bf16(kf[2 * ks], qr[ks], c0, 0, 0, 0);
;         c1 = __builtin_amdgcn_mfma_f32_32x32x16_bf16(kf[2 * ks + 1], qr[ks], c1, 0, 0, 0);
;     }
;     __builtin_amdgcn_sched_barrier(0);
;     { bf16x8 kg[4];
; #pragma unroll
;       for (int ks = 0; ks < 2; ++ks) { DSR128(kg[2 * ks], ka[2 + ks], 0); DSR128(kg[2 * ks + 1], ka[2 + ks], 4096); }
;       asm volatile("s_waitcnt lgkmcnt(0)" : "+v"(kg[0]), "+v"(kg[1]), "+v"(kg[2]), "+v"(kg[3]));
; #pragma unroll
;       for (int ks = 0; ks < 2; ++ks) {
;           c0 = __builtin_amdgcn_mfma_f32_32x32x16_bf16(kg[2 * ks], qr[2 + ks], c0, 0, 0, 0);
;           c1 = __builtin_amdgcn_mfma_f32_32x32x16_bf16(kg[2 * ks + 1], qr[2 + ks], c1, 0, 0, 0);
;       } }
;     __builtin_amdgcn_sched_barrier(0);
;     if (HAS_PREV) {
; #pragma unroll
;         for (int e = 0; e < 4; ++e) DSR128(vA[e], va[0], e * 4096);
;     }
;     float mx = fmaxf(c0[0], c1[0]);
; #pragma unroll
;     for (int i = 1; i < 16; ++i) mx = fmaxf(mx, fmaxf(c0[i], c1[i]));
;     mx = swap_max(mx);
;     float a = 1.0f;
;     ...
;     { u32x4 w;
;       w.x = pg8::cvt_pk_bf16(c0[0], c0[1]); w.y = pg8::cvt_pk_bf16(c0[2], c0[3]); w.z = pg8::cvt_pk_bf16(c0[4], c0[5]); w.w = pg8::cvt_pk_bf16(c0[6], c0[7]); pbp[0] = __builtin_bit_cast(bf16x8, w);
;       w.x = pg8::cvt_pk_bf16(c0[8], c0[9]); w.y = pg8::cvt_pk_bf16(c0[10], c0[11]); w.z = pg8::cvt_pk_bf16(c0[12], c0[13]); w.w = pg8::cvt_pk_bf16(c0[14], c0[15]); pbp[1] = __builtin_bit_cast(bf16x8, w);
;       w.x = pg8::cvt_pk_bf16(c1[0], c1[1]); w.y = pg8::cvt_pk_bf16(c1[2], c1[3]); w.z = pg8::cvt_pk_bf16(c1[4], c1[5]); w.w = pg8::cvt_pk_bf16(c1[6], c1[7]); pbp[2] = __builtin_bit_cast(bf16x8, w);
;       w.x = pg8::cvt_pk_bf16(c1[8], c1[9]); w.y = pg8::cvt_pk_bf16(c1[10], c1[11]); w.z = pg8::cvt_pk_bf16(c1[12], c1[13]); w.w = pg8::cvt_pk_bf16(c1[14], c1[15]); pbp[3] = __builtin_bit_cast(bf16x8, w); }
.Lu3_wd_2:
	s_barrier
	s_add_u32 s46, s46, 0x4000
	s_addc_u32 s47, s47, 0
	s_add_i32 s53, s53, 1
	s_add_u32 s54, s54, 0x10000
	s_addc_u32 s55, s55, 0
	s_add_u32 s56, s56, 0x4000
	s_addc_u32 s57, s57, 0
	v_cvt_pk_bf16_f32 v124, v80, v81
	v_cvt_pk_bf16_f32 v125, v82, v83
	v_cvt_pk_bf16_f32 v126, v84, v85
	v_cvt_pk_bf16_f32 v127, v86, v87
	v_cvt_pk_bf16_f32 v120, v88, v89
	v_cvt_pk_bf16_f32 v121, v90, v91
	v_cvt_pk_bf16_f32 v122, v92, v93
	v_cvt_pk_bf16_f32 v123, v94, v95
	v_cvt_pk_bf16_f32 v116, v64, v65
	v_cvt_pk_bf16_f32 v117, v66, v67
	v_cvt_pk_bf16_f32 v118, v68, v69
	v_cvt_pk_bf16_f32 v119, v70, v71
	v_cvt_pk_bf16_f32 v112, v72, v73
	v_cvt_pk_bf16_f32 v113, v74, v75
	v_cvt_pk_bf16_f32 v114, v76, v77
	v_cvt_pk_bf16_f32 v115, v78, v79
	s_mov_b32 s51, 0
	ds_read_b128 v[128:131], v209 offset:0
	ds_read_b128 v[132:135], v209 offset:4096
	ds_read_b128 v[136:139], v211 offset:0
	ds_read_b128 v[140:143], v211 offset:4096
	ds_read_b128 v[222:225], v213 offset:0
	ds_read_b128 v[226:229], v213 offset:4096
	ds_read_b128 v[230:233], v215 offset:0
	ds_read_b128 v[234:237], v215 offset:4096
	s_waitcnt lgkmcnt(4)
	v_mfma_f32_32x32x16_bf16 v[80:95], v[128:131], v[96:99], v[158:173]
	v_mfma_f32_32x32x16_bf16 v[64:79], v[132:135], v[96:99], v[158:173]
	v_mfma_f32_32x32x16_bf16 v[80:95], v[136:139], v[100:103], v[80:95]
	v_mfma_f32_32x32x16_bf16 v[64:79], v[140:143], v[100:103], v[64:79]
	s_waitcnt lgkmcnt(0)
	v_mfma_f32_32x32x16_bf16 v[80:95], v[222:225], v[104:107], v[80:95]
	v_mfma_f32_32x32x16_bf16 v[64:79], v[226:229], v[104:107], v[64:79]
	v_mfma_f32_32x32x16_bf16 v[80:95], v[230:233], v[108:111], v[80:95]
	v_mfma_f32_32x32x16_bf16 v[64:79], v[234:237], v[108:111], v[64:79]
	ds_read_b128 v[140:143], v174 offset:32768
	ds_read_b128 v[136:139], v174 offset:36864
	ds_read_b128 v[132:135], v174 offset:40960
	ds_read_b128 v[128:131], v174 offset:45056
	s_nop 6
	v_max3_f32 v202, v80, v81, v82
	v_max3_f32 v202, v202, v83, v84
	v_max3_f32 v202, v202, v85, v86
	v_max3_f32 v202, v202, v87, v88
	v_max3_f32 v202, v202, v89, v90
	v_max3_f32 v202, v202, v91, v92
	v_max3_f32 v202, v202, v93, v94
	v_max3_f32 v204, v64, v65, v66
	v_max3_f32 v204, v204, v67, v68
	v_max3_f32 v204, v204, v69, v70
	v_max3_f32 v204, v204, v71, v72
	v_max3_f32 v204, v204, v73, v74
	v_max3_f32 v204, v204, v75, v76
	v_max3_f32 v204, v204, v77, v78
	v_max3_f32 v202, v202, v95, v79
	v_max_f32_e32 v202, v202, v204
	v_mov_b32_e32 v204, v202
	s_nop 1
	v_permlane32_swap_b32_e32 v202, v204
	v_max_f32_e32 v202, v202, v204
	v_cmp_lt_f32_e32 vcc, s84, v202
	s_cbranch_vccnz .Lu3_rare_0
.Lu3_c_0:
	v_exp_f32_e32 v80, v80
	v_exp_f32_e32 v81, v81
	v_exp_f32_e32 v82, v82
	ds_read_b128 v[222:225], v175 offset:32768
	ds_read_b128 v[226:229], v175 offset:36864
	ds_read_b128 v[230:233], v175 offset:40960
	ds_read_b128 v[234:237], v175 offset:45056
	s_waitcnt lgkmcnt(4)
	v_exp_f32_e32 v83, v83
	v_mfma_f32_32x32x16_bf16 v[48:63], v[140:143], v[124:127], v[48:63]
	v_exp_f32_e32 v84, v84
	v_exp_f32_e32 v85, v85
	v_exp_f32_e32 v86, v86
	v_exp_f32_e32 v87, v87
	v_mfma_f32_32x32x16_bf16 v[32:47], v[136:139], v[124:127], v[32:47]
	v_add_f32_e32 v192, v80, v81
	v_add_f32_e32 v192, v82, v192
	v_add_f32_e32 v192, v83, v192
	v_mfma_f32_32x32x16_bf16 v[16:31], v[132:135], v[124:127], v[16:31]
	v_add_f32_e32 v192, v84, v192
	v_add_f32_e32 v192, v85, v192
	v_add_f32_e32 v192, v86, v192
	v_add_f32_e32 v192, v87, v192
	v_mfma_f32_32x32x16_bf16 v[0:15], v[128:131], v[124:127], v[0:15]
	s_cmp_gt_u32 s53, 29
	s_cbranch_scc1 .Lu3_nok_0
	s_add_i32 m0, s33, 0x4000
	s_nop 0
	global_load_lds_dwordx4 v193, s[54:55]
.Lu3_nok_0:
	v_exp_f32_e32 v88, v88
	v_exp_f32_e32 v89, v89
	v_exp_f32_e32 v90, v90
	v_exp_f32_e32 v91, v91
	ds_read_b128 v[124:127], v178 offset:32768
	ds_read_b128 v[128:131], v178 offset:36864
	ds_read_b128 v[132:135], v178 offset:40960
	ds_read_b128 v[136:139], v178 offset:45056
	s_waitcnt lgkmcnt(4)
	v_add_f32_e32 v192, v192, v88
	v_mfma_f32_32x32x16_bf16 v[48:63], v[222:225], v[120:123], v[48:63]
	v_exp_f32_e32 v92, v92
	v_add_f32_e32 v192, v89, v192
	v_exp_f32_e32 v93, v93
	v_add_f32_e32 v192, v90, v192
	v_exp_f32_e32 v94, v94
	v_add_f32_e32 v192, v91, v192
	v_exp_f32_e32 v95, v95
	v_mfma_f32_32x32x16_bf16 v[32:47], v[226:229], v[120:123], v[32:47]
	v_add_f32_e32 v192, v92, v192
	v_add_f32_e32 v192, v93, v192
	v_add_f32_e32 v192, v94, v192
	v_add_f32_e32 v192, v95, v192
	v_mfma_f32_32x32x16_bf16 v[16:31], v[230:233], v[120:123], v[16:31]
	v_mfma_f32_32x32x16_bf16 v[0:15], v[234:237], v[120:123], v[0:15]
	s_cmp_eq_u32 s46, 0x78000
	s_cbranch_scc1 .Lu3_nov_0
	s_add_i32 m0, s33, 0xa000
	s_nop 0
	global_load_lds_dwordx4 v182, s[56:57]
	s_add_i32 m0, s33, 0xc000
	s_nop 0
	global_load_lds_dwordx4 v183, s[56:57]
.Lu3_nov_0:
	v_exp_f32_e32 v64, v64
	v_exp_f32_e32 v65, v65
	v_exp_f32_e32 v66, v66
	ds_read_b128 v[120:123], v179 offset:32768
	ds_read_b128 v[140:143], v179 offset:36864
	ds_read_b128 v[222:225], v179 offset:40960
	ds_read_b128 v[226:229], v179 offset:45056
	s_waitcnt lgkmcnt(4)
	v_exp_f32_e32 v67, v67
	v_mfma_f32_32x32x16_bf16 v[48:63], v[124:127], v[116:119], v[48:63]
	v_add_f32_e32 v192, v192, v64
	v_exp_f32_e32 v68, v68
	v_add_f32_e32 v192, v65, v192
	v_exp_f32_e32 v69, v69
	v_add_f32_e32 v192, v66, v192
	v_exp_f32_e32 v70, v70
	v_add_f32_e32 v192, v67, v192
	v_mfma_f32_32x32x16_bf16 v[32:47], v[128:131], v[116:119], v[32:47]
	v_exp_f32_e32 v71, v71
	v_add_f32_e32 v192, v68, v192
	v_add_f32_e32 v192, v69, v192
	v_add_f32_e32 v192, v70, v192
	v_add_f32_e32 v192, v71, v192
	v_mfma_f32_32x32x16_bf16 v[16:31], v[132:135], v[116:119], v[16:31]
	v_mfma_f32_32x32x16_bf16 v[0:15], v[136:139], v[116:119], v[0:15]
	v_exp_f32_e32 v72, v72
	v_exp_f32_e32 v73, v73
	v_exp_f32_e32 v74, v74
	v_exp_f32_e32 v75, v75
	s_waitcnt lgkmcnt(0)
	v_add_f32_e32 v192, v192, v72
	v_mfma_f32_32x32x16_bf16 v[48:63], v[120:123], v[112:115], v[48:63]
	v_exp_f32_e32 v76, v76
	v_add_f32_e32 v192, v73, v192
	v_exp_f32_e32 v77, v77
	v_add_f32_e32 v192, v74, v192
	v_exp_f32_e32 v78, v78
	v_add_f32_e32 v192, v75, v192
	v_exp_f32_e32 v79, v79
	v_mfma_f32_32x32x16_bf16 v[32:47], v[140:143], v[112:115], v[32:47]
	v_add_f32_e32 v192, v76, v192
	v_add_f32_e32 v192, v77, v192
	v_add_f32_e32 v192, v78, v192
	v_add_f32_e32 v192, v79, v192
	v_mfma_f32_32x32x16_bf16 v[16:31], v[222:225], v[112:115], v[16:31]
	v_mfma_f32_32x32x16_bf16 v[0:15], v[226:229], v[112:115], v[0:15]
	s_cmp_lg_u32 s51, 0
	s_cbranch_scc1 .Lu3_resc_0
	v_add_f32_e32 v198, v198, v192

; template <bool FIRST, bool HAS_PREV> ...
;     ...
;     { const float dl = FIRST ? mx : ((mx > 8.0f) ? mx : 0.f);
;       if (FIRST || __any(dl != 0.f)) {
; #pragma unroll
;           for (int i = 0; i < 16; ++i) { c0[i] -= dl; c1[i] -= dl; }
;           st.mrun += dl; if (!FIRST) a = __builtin_amdgcn_exp2f(-dl);
;       } }
;     ...
;     st.l = st.l * a + ps;
;     if (!FIRST) { if (__any(a != 1.0f)) {
; #pragma unroll
;         for (int e = 0; e < 4; ++e)
; #pragma unroll
;             for (int i = 0; i < 16; ++i) o[e][i] *= a; } }
.Lu3_wd_0:
	s_barrier
	s_add_u32 s46, s46, 0x4000
	s_addc_u32 s47, s47, 0
	s_add_i32 s53, s53, 1
	s_add_u32 s54, s54, 0x10000
	s_addc_u32 s55, s55, 0
	s_add_u32 s56, s56, 0x4000
	s_addc_u32 s57, s57, 0
	v_cvt_pk_bf16_f32 v124, v80, v81
	v_cvt_pk_bf16_f32 v125, v82, v83
	v_cvt_pk_bf16_f32 v126, v84, v85
	v_cvt_pk_bf16_f32 v127, v86, v87
	v_cvt_pk_bf16_f32 v120, v88, v89
	v_cvt_pk_bf16_f32 v121, v90, v91
	v_cvt_pk_bf16_f32 v122, v92, v93
	v_cvt_pk_bf16_f32 v123, v94, v95
	v_cvt_pk_bf16_f32 v116, v64, v65
	v_cvt_pk_bf16_f32 v117, v66, v67
	v_cvt_pk_bf16_f32 v118, v68, v69
	v_cvt_pk_bf16_f32 v119, v70, v71
	v_cvt_pk_bf16_f32 v112, v72, v73
	v_cvt_pk_bf16_f32 v113, v74, v75
	v_cvt_pk_bf16_f32 v114, v76, v77
	v_cvt_pk_bf16_f32 v115, v78, v79
	s_branch .LBB0_561
.Lu3_rare_1:
	s_nop 1
	v_cndmask_b32_e32 v204, 0, v202, vcc
	s_mov_b32 s51, 1
	v_exp_f32_e64 v202, -v204
	v_sub_f32_e32 v80, v80, v204
	v_sub_f32_e32 v81, v81, v204
	v_sub_f32_e32 v82, v82, v204
	v_sub_f32_e32 v83, v83, v204
	v_sub_f32_e32 v84, v84, v204
	v_sub_f32_e32 v85, v85, v204
	v_sub_f32_e32 v86, v86, v204
	v_sub_f32_e32 v87, v87, v204
	v_sub_f32_e32 v88, v88, v204
	v_sub_f32_e32 v89, v89, v204
	v_sub_f32_e32 v90, v90, v204
	v_sub_f32_e32 v91, v91, v204
	v_sub_f32_e32 v92, v92, v204
	v_sub_f32_e32 v93, v93, v204
	v_sub_f32_e32 v94, v94, v204
	v_sub_f32_e32 v95, v95, v204
	v_sub_f32_e32 v79, v79, v204
	v_sub_f32_e32 v78, v78, v204
	v_sub_f32_e32 v77, v77, v204
	v_sub_f32_e32 v76, v76, v204
	v_sub_f32_e32 v75, v75, v204
	v_sub_f32_e32 v74, v74, v204
	v_sub_f32_e32 v73, v73, v204
	v_sub_f32_e32 v72, v72, v204
	v_sub_f32_e32 v71, v71, v204
	v_sub_f32_e32 v70, v70, v204
	v_sub_f32_e32 v69, v69, v204
	v_sub_f32_e32 v68, v68, v204
	v_sub_f32_e32 v67, v67, v204
	v_sub_f32_e32 v66, v66, v204
	v_sub_f32_e32 v65, v65, v204
	v_sub_f32_e32 v64, v64, v204
	v_add_f32_e32 v199, v199, v204
	s_nop 0
	v_xor_b32_e32 v158, 0x80000000, v199
	v_mov_b32_e32 v159, v158
	v_mov_b32_e32 v160, v158
	v_mov_b32_e32 v161, v158
	v_mov_b32_e32 v162, v158
	v_mov_b32_e32 v163, v158
	v_mov_b32_e32 v164, v158
	v_mov_b32_e32 v165, v158
	v_mov_b32_e32 v166, v158
	v_mov_b32_e32 v167, v158
	v_mov_b32_e32 v168, v158
	v_mov_b32_e32 v169, v158
	v_mov_b32_e32 v170, v158
	v_mov_b32_e32 v171, v158
	v_mov_b32_e32 v172, v158
	v_mov_b32_e32 v173, v158
	s_branch .Lu3_c_1
.Lu3_resc_1:
	v_pk_mul_f32 v[62:63], v[202:203], v[62:63] op_sel_hi:[0,1]
	v_pk_mul_f32 v[60:61], v[202:203], v[60:61] op_sel_hi:[0,1]
	v_pk_mul_f32 v[58:59], v[202:203], v[58:59] op_sel_hi:[0,1]
	v_pk_mul_f32 v[56:57], v[202:203], v[56:57] op_sel_hi:[0,1]
	v_pk_mul_f32 v[54:55], v[202:203], v[54:55] op_sel_hi:[0,1]
	v_pk_mul_f32 v[52:53], v[202:203], v[52:53] op_sel_hi:[0,1]
	v_pk_mul_f32 v[50:51], v[202:203], v[50:51] op_sel_hi:[0,1]
	v_pk_mul_f32 v[48:49], v[202:203], v[48:49] op_sel_hi:[0,1]
	v_pk_mul_f32 v[46:47], v[202:203], v[46:47] op_sel_hi:[0,1]
	v_pk_mul_f32 v[44:45], v[202:203], v[44:45] op_sel_hi:[0,1]
	v_pk_mul_f32 v[42:43], v[202:203], v[42:43] op_sel_hi:[0,1]
	v_pk_mul_f32 v[40:41], v[202:203], v[40:41] op_sel_hi:[0,1]
	v_pk_mul_f32 v[38:39], v[202:203], v[38:39] op_sel_hi:[0,1]
	v_pk_mul_f32 v[36:37], v[202:203], v[36:37] op_sel_hi:[0,1]
	v_pk_mul_f32 v[34:35], v[202:203], v[34:35] op_sel_hi:[0,1]
	v_pk_mul_f32 v[32:33], v[202:203], v[32:33] op_sel_hi:[0,1]
	v_pk_mul_f32 v[30:31], v[202:203], v[30:31] op_sel_hi:[0,1]
	v_pk_mul_f32 v[28:29], v[202:203], v[28:29] op_sel_hi:[0,1]
	v_pk_mul_f32 v[26:27], v[202:203], v[26:27] op_sel_hi:[0,1]
	v_pk_mul_f32 v[24:25], v[202:203], v[24:25] op_sel_hi:[0,1]
	v_pk_mul_f32 v[22:23], v[202:203], v[22:23] op_sel_hi:[0,1]
	v_pk_mul_f32 v[20:21], v[202:203], v[20:21] op_sel_hi:[0,1]
	v_pk_mul_f32 v[18:19], v[202:203], v[18:19] op_sel_hi:[0,1]
	v_pk_mul_f32 v[16:17], v[202:203], v[16:17] op_sel_hi:[0,1]
	v_pk_mul_f32 v[14:15], v[202:203], v[14:15] op_sel_hi:[0,1]
	v_pk_mul_f32 v[12:13], v[202:203], v[12:13] op_sel_hi:[0,1]
	v_pk_mul_f32 v[10:11], v[202:203], v[10:11] op_sel_hi:[0,1]
	v_pk_mul_f32 v[8:9], v[202:203], v[8:9] op_sel_hi:[0,1]
	v_pk_mul_f32 v[6:7], v[202:203], v[6:7] op_sel_hi:[0,1]
	v_pk_mul_f32 v[4:5], v[202:203], v[4:5] op_sel_hi:[0,1]
	v_pk_mul_f32 v[2:3], v[202:203], v[2:3] op_sel_hi:[0,1]
	v_pk_mul_f32 v[0:1], v[202:203], v[0:1] op_sel_hi:[0,1]
	v_fmac_f32_e32 v192, v198, v202
	s_nop 0
	v_mov_b32_e32 v198, v192
	s_branch .Lu3_e_1

; #define LAS __attribute__((address_space(3)))
; __device__ __forceinline__ float swap_sum(float m) { auto rr = __builtin_amdgcn_permlane32_swap(__float_as_uint(m), __float_as_uint(m), false, false); return __uint_as_float(rr[0]) + __uint_as_float(rr[1]); }
; #define ATT_WAITBAR(N) do { asm volatile("s_waitcnt vmcnt(" #N ") lgkmcnt(0)" ::: "memory"); __builtin_amdgcn_s_barrier(); asm volatile("" ::: "memory"); } while (0)
; __device__ __forceinline__ void attn_unit(LAS unsigned char* lds, const bf16* __restrict__ Qb, const bf16* __restrict__ Kb, const bf16* __restrict__ VT, bf16* __restrict__ Y,
;                                           const float* __restrict__ gsub, float lam, int b, int h, int qb, float* o1scr) {
;     ...
;         { const LAS unsigned char* vb = lds + VB0 + 1 * VSL;
; #pragma unroll
;           for (int e = 0; e < 4; ++e)
; #pragma unroll
;               for (int kk = 0; kk < 4; ++kk) { const bf16x8 vf = *(const LAS bf16x8*)(vb + e * 4096 + vofs[kk]);
;                   o[e] = __builtin_amdgcn_mfma_f32_32x32x16_bf16(vf, pbp[kk], o[e], 0, 0, 0); } }
;         ATT_WAITBAR(0);
;         inv = 1.0f / swap_sum(st.l);
;         if (mp == 0) {
; #pragma unroll
;             for (int e = 0; e < 4; ++e)
; #pragma unroll
;                 for (int a = 0; a < 4; ++a) { f32x4 v = {o[e][4 * a] * inv, o[e][4 * a + 1] * inv, o[e][4 * a + 2] * inv, o[e][4 * a + 3] * inv};
;                     *(f32x4*)(o1scr + ((size_t)(e * 4 + a) * 512 + tid) * 4) = v; }
;         }
.Lu3_exit:
	v_mov_b32_e32 v128, v198
.LBB0_576:
	v_add_u32_e32 v84, 0, v210
	ds_read_b128 v[64:67], v84 offset:40960
	ds_read_b128 v[68:71], v84 offset:45056
	v_add_u32_e32 v85, 0, v212
	v_add_u32_e32 v86, 0, v214
	v_add_u32_e32 v87, 0, v216
	s_mov_b64 s[46:47], -1
	s_waitcnt lgkmcnt(0)
	v_mfma_f32_32x32x16_bf16 v[48:63], v[64:67], v[124:127], v[48:63]
	ds_read_b128 v[64:67], v85 offset:40960
	ds_read_b128 v[72:75], v85 offset:45056
	ds_read_b128 v[76:79], v86 offset:45056
	s_waitcnt lgkmcnt(0)
	v_mfma_f32_32x32x16_bf16 v[48:63], v[64:67], v[120:123], v[48:63]
	ds_read_b128 v[64:67], v86 offset:40960
	s_waitcnt lgkmcnt(0)
	v_mfma_f32_32x32x16_bf16 v[48:63], v[64:67], v[116:119], v[48:63]
	ds_read_b128 v[64:67], v87 offset:40960
	ds_read_b128 v[80:83], v87 offset:45056
	s_waitcnt lgkmcnt(0)
	v_mfma_f32_32x32x16_bf16 v[48:63], v[64:67], v[112:115], v[48:63]
	v_mfma_f32_32x32x16_bf16 v[32:47], v[68:71], v[124:127], v[32:47]
	ds_read_b128 v[64:67], v84 offset:49152
	ds_read_b128 v[68:71], v84 offset:53248
	s_waitcnt lgkmcnt(0)
	v_mfma_f32_32x32x16_bf16 v[16:31], v[64:67], v[124:127], v[16:31]
	v_mfma_f32_32x32x16_bf16 v[32:47], v[72:75], v[120:123], v[32:47]
	ds_read_b128 v[64:67], v85 offset:49152
	ds_read_b128 v[72:75], v85 offset:53248
	s_waitcnt lgkmcnt(0)
	v_mfma_f32_32x32x16_bf16 v[16:31], v[64:67], v[120:123], v[16:31]
	v_mfma_f32_32x32x16_bf16 v[0:15], v[68:71], v[124:127], v[0:15]
	v_mfma_f32_32x32x16_bf16 v[32:47], v[76:79], v[116:119], v[32:47]
	ds_read_b128 v[64:67], v86 offset:49152
	ds_read_b128 v[76:79], v86 offset:53248
	s_waitcnt lgkmcnt(0)
	v_mfma_f32_32x32x16_bf16 v[16:31], v[64:67], v[116:119], v[16:31]
	v_mfma_f32_32x32x16_bf16 v[0:15], v[72:75], v[120:123], v[0:15]
	v_mfma_f32_32x32x16_bf16 v[32:47], v[80:83], v[112:115], v[32:47]
	ds_read_b128 v[64:67], v87 offset:49152
	ds_read_b128 v[82:85], v87 offset:53248
	s_waitcnt vmcnt(0) lgkmcnt(0)
	s_barrier
	s_waitcnt lgkmcnt(0)
	v_mfma_f32_32x32x16_bf16 v[16:31], v[64:67], v[112:115], v[16:31]
	v_mov_b32_e32 v64, v128
	s_nop 1
	v_permlane32_swap_b32_e32 v128, v64
	v_add_f32_e32 v64, v128, v64
	v_div_scale_f32 v65, s[10:11], v64, v64, 1.0
	v_rcp_f32_e32 v66, v65
	v_mfma_f32_32x32x16_bf16 v[0:15], v[76:79], v[116:119], v[0:15]
	v_fma_f32 v67, -v65, v66, 1.0
	v_fmac_f32_e32 v66, v67, v66
	v_div_scale_f32 v67, vcc, 1.0, v64, 1.0
	v_mul_f32_e32 v68, v67, v66
	v_mfma_f32_32x32x16_bf16 v[0:15], v[82:85], v[112:115], v[0:15]
	v_fma_f32 v69, -v65, v68, v67
	v_fmac_f32_e32 v68, v69, v66
	v_fma_f32 v65, -v65, v68, v67
	v_div_fmas_f32 v65, v65, v66, v68
	v_div_fixup_f32 v80, v65, v64, 1.0
	s_and_b64 vcc, exec, s[0:1]
	s_cbranch_vccz .LBB0_559
	v_pk_mul_f32 v[64:65], v[48:49], v[80:81] op_sel_hi:[1,0]
	v_pk_mul_f32 v[66:67], v[50:51], v[80:81] op_sel_hi:[1,0]
	v_lshlrev_b32_e32 v70, 4, v156
	global_store_dwordx4 v70, v[64:67], s[8:9]
	s_mov_b64 s[46:47], 0
	s_nop 0
	v_pk_mul_f32 v[64:65], v[52:53], v[80:81] op_sel_hi:[1,0]
	v_pk_mul_f32 v[66:67], v[54:55], v[80:81] op_sel_hi:[1,0]
	v_add_u32_e32 v69, 0x2000, v70
	global_store_dwordx4 v69, v[64:67], s[8:9]
	s_nop 1
	v_pk_mul_f32 v[64:65], v[56:57], v[80:81] op_sel_hi:[1,0]
	v_pk_mul_f32 v[66:67], v[58:59], v[80:81] op_sel_hi:[1,0]
	v_add_u32_e32 v68, 0x4000, v70
	global_store_dwordx4 v68, v[64:67], s[8:9]
	s_nop 1
	v_pk_mul_f32 v[64:65], v[60:61], v[80:81] op_sel_hi:[1,0]
	v_pk_mul_f32 v[66:67], v[62:63], v[80:81] op_sel_hi:[1,0]
	v_add_u32_e32 v69, 0x6000, v70
	global_store_dwordx4 v69, v[64:67], s[8:9]
	s_nop 1
	v_pk_mul_f32 v[64:65], v[32:33], v[80:81] op_sel_hi:[1,0]
	v_pk_mul_f32 v[66:67], v[34:35], v[80:81] op_sel_hi:[1,0]
	v_add_u32_e32 v68, 0x8000, v70
	global_store_dwordx4 v68, v[64:67], s[8:9]
	s_nop 1
	v_pk_mul_f32 v[64:65], v[36:37], v[80:81] op_sel_hi:[1,0]
	v_pk_mul_f32 v[66:67], v[38:39], v[80:81] op_sel_hi:[1,0]
	v_add_u32_e32 v69, 0xa000, v70
	global_store_dwordx4 v69, v[64:67], s[8:9]
	s_nop 1
	v_pk_mul_f32 v[64:65], v[40:41], v[80:81] op_sel_hi:[1,0]
	v_pk_mul_f32 v[66:67], v[42:43], v[80:81] op_sel_hi:[1,0]
	v_add_u32_e32 v68, 0xc000, v70
	global_store_dwordx4 v68, v[64:67], s[8:9]
	s_nop 1
	v_pk_mul_f32 v[64:65], v[44:45], v[80:81] op_sel_hi:[1,0]
	v_pk_mul_f32 v[66:67], v[46:47], v[80:81] op_sel_hi:[1,0]
	v_add_u32_e32 v69, 0xe000, v70
	global_store_dwordx4 v69, v[64:67], s[8:9]
	s_nop 1
	v_pk_mul_f32 v[64:65], v[16:17], v[80:81] op_sel_hi:[1,0]
	v_pk_mul_f32 v[66:67], v[18:19], v[80:81] op_sel_hi:[1,0]
	v_add_u32_e32 v68, 0x10000, v70
	global_store_dwordx4 v68, v[64:67], s[8:9]
	s_nop 1
	v_pk_mul_f32 v[64:65], v[20:21], v[80:81] op_sel_hi:[1,0]
	v_pk_mul_f32 v[66:67], v[22:23], v[80:81] op_sel_hi:[1,0]
	v_add_u32_e32 v69, 0x12000, v70
	global_store_dwordx4 v69, v[64:67], s[8:9]
	s_nop 1
	v_pk_mul_f32 v[64:65], v[24:25], v[80:81] op_sel_hi:[1,0]
	v_pk_mul_f32 v[66:67], v[26:27], v[80:81] op_sel_hi:[1,0]
	v_add_u32_e32 v68, 0x14000, v70
	global_store_dwordx4 v68, v[64:67], s[8:9]
	s_nop 1
	v_pk_mul_f32 v[64:65], v[28:29], v[80:81] op_sel_hi:[1,0]
	v_pk_mul_f32 v[66:67], v[30:31], v[80:81] op_sel_hi:[1,0]
	v_add_u32_e32 v69, 0x16000, v70
	global_store_dwordx4 v69, v[64:67], s[8:9]
	s_nop 1
	v_pk_mul_f32 v[64:65], v[0:1], v[80:81] op_sel_hi:[1,0]
	v_pk_mul_f32 v[66:67], v[2:3], v[80:81] op_sel_hi:[1,0]
	v_add_u32_e32 v68, 0x18000, v70
	global_store_dwordx4 v68, v[64:67], s[8:9]
	s_nop 1
	v_pk_mul_f32 v[64:65], v[4:5], v[80:81] op_sel_hi:[1,0]
	v_pk_mul_f32 v[66:67], v[6:7], v[80:81] op_sel_hi:[1,0]
	v_add_u32_e32 v69, 0x1a000, v70
	global_store_dwordx4 v69, v[64:67], s[8:9]
	s_nop 1
	v_pk_mul_f32 v[64:65], v[8:9], v[80:81] op_sel_hi:[1,0]
	v_pk_mul_f32 v[66:67], v[10:11], v[80:81] op_sel_hi:[1,0]
	v_add_u32_e32 v68, 0x1c000, v70
	global_store_dwordx4 v68, v[64:67], s[8:9]
	s_nop 1
	v_pk_mul_f32 v[64:65], v[12:13], v[80:81] op_sel_hi:[1,0]
	v_pk_mul_f32 v[66:67], v[14:15], v[80:81] op_sel_hi:[1,0]
	v_add_u32_e32 v69, 0x1e000, v70
	global_store_dwordx4 v69, v[64:67], s[8:9]
	s_branch .LBB0_559

; __global__ void __launch_bounds__(512, 2) fwd_mega(Args a) {
	.amdhsa_kernel _Z8fwd_mega4Args
		.amdhsa_group_segment_fixed_size 0
		.amdhsa_private_segment_fixed_size 0
		.amdhsa_kernarg_size 480
		.amdhsa_user_sgpr_count 2
		.amdhsa_user_sgpr_dispatch_ptr 0
		.amdhsa_user_sgpr_queue_ptr 0
		.amdhsa_user_sgpr_kernarg_segment_ptr 1
		.amdhsa_user_sgpr_dispatch_id 0
		.amdhsa_user_sgpr_kernarg_preload_length 0
		.amdhsa_user_sgpr_kernarg_preload_offset 0
		.amdhsa_user_sgpr_private_segment_size 0
		.amdhsa_uses_dynamic_stack 0
		.amdhsa_enable_private_segment 0
		.amdhsa_system_sgpr_workgroup_id_x 1
		.amdhsa_system_sgpr_workgroup_id_y 0
		.amdhsa_system_sgpr_workgroup_id_z 0
		.amdhsa_system_sgpr_workgroup_info 0
		.amdhsa_system_vgpr_workitem_id 2
		.amdhsa_next_free_vgpr 240
		.amdhsa_next_free_sgpr 102
		.amdhsa_accum_offset 240
		.amdhsa_reserve_vcc 1
		.amdhsa_float_round_mode_32 0
		.amdhsa_float_round_mode_16_64 0
		.amdhsa_float_denorm_mode_32 3
		.amdhsa_float_denorm_mode_16_64 3
		.amdhsa_dx10_clamp 1
		.amdhsa_ieee_mode 1
		.amdhsa_fp16_overflow 0
		.amdhsa_tg_split 0
		.amdhsa_exception_fp_ieee_invalid_op 0
		.amdhsa_exception_fp_denorm_src 0
		.amdhsa_exception_fp_ieee_div_zero 0
		.amdhsa_exception_fp_ieee_overflow 0
		.amdhsa_exception_fp_ieee_underflow 0
		.amdhsa_exception_fp_ieee_inexact 0
		.amdhsa_exception_int_div_zero 0
	.end_amdhsa_kernel

; __global__ void __launch_bounds__(512, 2) fwd_mega(Args a) {
.Lfunc_end0:
	.size	_Z8fwd_mega4Args, .Lfunc_end0-_Z8fwd_mega4Args
	.set _Z8fwd_mega4Args.num_vgpr, 240
	.set _Z8fwd_mega4Args.num_agpr, 0
	.set _Z8fwd_mega4Args.numbered_sgpr, 102
	.set _Z8fwd_mega4Args.num_named_barrier, 0
	.set _Z8fwd_mega4Args.private_seg_size, 0
	.set _Z8fwd_mega4Args.uses_vcc, 1
	.set _Z8fwd_mega4Args.uses_flat_scratch, 0
	.set _Z8fwd_mega4Args.has_dyn_sized_stack, 0
	.set _Z8fwd_mega4Args.has_recursion, 0
	.set _Z8fwd_mega4Args.has_indirect_call, 0

; __global__ void __launch_bounds__(512, 2) fwd_mega(Args a) {
amdhsa.kernels:
  - .agpr_count:     0
    .args:
      - .offset:         0
        .size:           224
        .value_kind:     by_value
      - .offset:         224
        .size:           4
        .value_kind:     hidden_block_count_x
      - .offset:         228
        .size:           4
        .value_kind:     hidden_block_count_y
      - .offset:         232
        .size:           4
        .value_kind:     hidden_block_count_z
      - .offset:         236
        .size:           2
        .value_kind:     hidden_group_size_x
      - .offset:         238
        .size:           2
        .value_kind:     hidden_group_size_y
      - .offset:         240
        .size:           2
        .value_kind:     hidden_group_size_z
      - .offset:         242
        .size:           2
        .value_kind:     hidden_remainder_x
      - .offset:         244
        .size:           2
        .value_kind:     hidden_remainder_y
      - .offset:         246
        .size:           2
        .value_kind:     hidden_remainder_z
      - .offset:         264
        .size:           8
        .value_kind:     hidden_global_offset_x
      - .offset:         272
        .size:           8
        .value_kind:     hidden_global_offset_y
      - .offset:         280
        .size:           8
        .value_kind:     hidden_global_offset_z
      - .offset:         288
        .size:           2
        .value_kind:     hidden_grid_dims
      - .offset:         312
        .size:           8
        .value_kind:     hidden_multigrid_sync_arg
      - .offset:         344
        .size:           4
        .value_kind:     hidden_dynamic_lds_size
    .group_segment_fixed_size: 0
    .kernarg_segment_align: 8
    .kernarg_segment_size: 480
    .language:       OpenCL C
    .language_version:
      - 2
      - 0
    .max_flat_workgroup_size: 512
    .name:           _Z8fwd_mega4Args
    .private_segment_fixed_size: 0
    .sgpr_count:     108
    .sgpr_spill_count: 14
    .symbol:         _Z8fwd_mega4Args.kd
    .uniform_work_group_size: 1
    .uses_dynamic_stack: false
    .vgpr_count:     240
    .vgpr_spill_count: 0
    .wavefront_size: 64
